# v80 + mix_o/ffn_out residual epilogues: second-half residual rows requested at epilogue start into dead registers (latency hidden behind first half)
# baseline (speedup 1.0000x reference)
; #define LAS __attribute__((address_space(3)))
; __device__ __forceinline__ void unpack8(const u32x4 w, float (&v)[8]) { v[0] = bflo(w.x); v[1] = bfhi(w.x); v[2] = bflo(w.y); v[3] = bfhi(w.y); v[4] = bflo(w.z); v[5] = bfhi(w.z); v[6] = bflo(w.w); v[7] = bfhi(w.w); }
; __device__ __forceinline__ u32x4 pack8(const float (&v)[8]) { u32x4 w; w.x = pk2(v[0], v[1]); w.y = pk2(v[2], v[3]); w.z = pk2(v[4], v[5]); w.w = pk2(v[6], v[7]); return w; }
;     __device__ __forceinline__ void row_group(Acc& acc, const int ai, const int m, const float (&xo0)[8], const float (&xo1)[8], bf16_t* xb0, const int row0, const int pn, const int wc, const int fq) const {
;         float ssq = 0.f;
; #pragma unroll
;         for (int bj = 0; bj < 2; ++bj) {
;             float v[8];
; #pragma unroll
;             for (int e = 0; e < 4; ++e) { const float a0 = bj ? xo1[e] : xo0[e], a1 = bj ? xo1[4 + e] : xo0[4 + e]; v[e] = dry ? a0 : a0 + acc[ai][bj][m][0][e]; v[4 + e] = dry ? a1 : a1 + acc[ai][bj][m][1][e]; }
; #pragma unroll
;             for (int e = 0; e < 8; ++e) ssq += v[e] * v[e];
;             gst<u32x4>(xb0 + (size_t)(ai * HALF + m * 16) * DM + bj * HALF, pack8(v));
;         }
;         ssq = xsum32p(xsum16p(ssq));
;         if (fq == 0) gst<float>(ss_next + (size_t)(row0 + ai * HALF + m * 16) * 16 + pn * 4 + wc, ssq);
;     }
;     __device__ __forceinline__ bool operator()(Acc& acc, const Unit& u, int wr, int wc, int fr, int fq, const LAS float*) const {
;         const int row0 = u.pm * BM + wr * 64 + fr, col0 = u.pn * BM + wc * 32 + 8 * fq;
;         bf16_t* xb0 = XB + (size_t)row0 * DM + col0; const float* xi0 = Xin + (size_t)row0 * DM + col0;
; #pragma unroll
;         for (int ai = 0; ai < 2; ++ai) {
;             u32x4 xv[4][2];
; #pragma unroll
;             for (int m = 0; m < 4; ++m)
; #pragma unroll
;                 for (int bj = 0; bj < 2; ++bj) xv[m][bj] = gld<u32x4>(xb0 + (size_t)(ai * HALF + m * 16) * DM + bj * HALF);
; #pragma unroll
;             for (int m = 0; m < 4; ++m) {
;                 float x0[8], x1[8]; unpack8(xv[m][0], x0); unpack8(xv[m][1], x1);
;                 row_group(acc, ai, m, x0, x1, xb0, row0, u.pn, wc, fq);
.LBB0_1238:
	v_mov_b32_e32 v130, v1
	s_lshl_b32 s2, s58, 8
	v_mbcnt_lo_u32_b32 v130, -1, v130
	v_mbcnt_hi_u32_b32 v130, -1, v130
	v_readlane_b32 s3, v250, 1
	v_bfe_u32 v163, v130, 4, 2
	s_add_i32 s2, s2, s3
	v_and_or_b32 v154, v130, 15, s2
	v_lshlrev_b32_e32 v130, 3, v163
	v_lshl_or_b32 v130, s57, 8, v130
	v_readlane_b32 s2, v250, 3
	v_ashrrev_i32_e32 v155, 31, v154
	v_lshlrev_b64 v[132:133], 11, v[154:155]
	v_or_b32_e32 v130, s2, v130
	v_readlane_b32 s2, v254, 49
	v_readlane_b32 s3, v254, 50
	v_ashrrev_i32_e32 v131, 31, v130
	s_lshl_b32 s8, s57, 2
	v_lshl_add_u64 v[132:133], s[2:3], 0, v[132:133]
	v_lshl_add_u64 v[156:157], v[130:131], 1, v[132:133]
	global_load_dwordx4 v[164:167], v[156:157], off
	global_load_dwordx4 v[168:171], v[156:157], off offset:256
	s_mov_b32 s2, 0x8000
	v_add_co_u32_e32 v130, vcc, s2, v156
	s_mov_b32 s2, 0x10000
	s_nop 0
	v_addc_co_u32_e32 v131, vcc, 0, v157, vcc
	v_add_co_u32_e32 v132, vcc, s2, v156
	s_mov_b32 s2, 0x18000
	s_nop 0
	v_addc_co_u32_e32 v133, vcc, 0, v157, vcc
	v_add_co_u32_e32 v172, vcc, s2, v156
	s_ashr_i32 s9, s8, 31
	s_nop 0
	v_addc_co_u32_e32 v173, vcc, 0, v157, vcc
	global_load_dwordx4 v[150:153], v[130:131], off
	global_load_dwordx4 v[146:149], v[130:131], off offset:256
	global_load_dwordx4 v[142:145], v[132:133], off
	global_load_dwordx4 v[138:141], v[132:133], off offset:256
	global_load_dwordx4 v[134:137], v[172:173], off
	s_nop 0
	global_load_dwordx4 v[130:133], v[172:173], off offset:256
	v_mov_b32_e32 v218, 0x40000
	v_mov_b32_e32 v219, 0
	v_lshl_add_u64 v[196:197], v[156:157], 0, v[218:219]
	global_load_dwordx4 v[180:183], v[196:197], off
	global_load_dwordx4 v[184:187], v[196:197], off offset:256
	v_mov_b32_e32 v218, 0x8000
	v_lshl_add_u64 v[196:197], v[196:197], 0, v[218:219]
	global_load_dwordx4 v[188:191], v[196:197], off
	global_load_dwordx4 v[192:195], v[196:197], off offset:256
	v_lshl_add_u64 v[196:197], v[196:197], 0, v[218:219]
	global_load_dwordx4 v[200:203], v[196:197], off
	global_load_dwordx4 v[206:209], v[196:197], off offset:256
	v_lshl_add_u64 v[196:197], v[196:197], 0, v[218:219]
	global_load_dwordx4 v[210:213], v[196:197], off
	global_load_dwordx4 v[214:217], v[196:197], off offset:256
	v_cmp_eq_u32_e64 s[2:3], 0, v163
	s_waitcnt vmcnt(15)
	v_lshlrev_b32_e32 v172, 16, v164
	v_and_b32_e32 v173, 0xffff0000, v164
	v_lshlrev_b32_e32 v174, 16, v166
	v_and_b32_e32 v175, 0xffff0000, v166
	v_lshlrev_b32_e32 v164, 16, v165
	v_and_b32_e32 v165, 0xffff0000, v165
	v_lshlrev_b32_e32 v166, 16, v167
	v_and_b32_e32 v167, 0xffff0000, v167
	s_waitcnt vmcnt(14)
	v_lshlrev_b32_e32 v176, 16, v168
	v_and_b32_e32 v177, 0xffff0000, v168
	v_lshlrev_b32_e32 v178, 16, v170
	v_and_b32_e32 v179, 0xffff0000, v170
	v_lshlrev_b32_e32 v168, 16, v169
	v_and_b32_e32 v169, 0xffff0000, v169
	v_lshlrev_b32_e32 v170, 16, v171
	v_and_b32_e32 v171, 0xffff0000, v171
	v_pk_add_f32 v[126:127], v[126:127], v[172:173]
	v_pk_add_f32 v[122:123], v[122:123], v[174:175]
	v_pk_add_f32 v[128:129], v[128:129], v[164:165]
	v_pk_add_f32 v[124:125], v[124:125], v[166:167]
	v_pk_add_f32 v[164:165], v[114:115], v[178:179]
	v_pk_add_f32 v[120:121], v[120:121], v[168:169]
	v_pk_add_f32 v[166:167], v[116:117], v[170:171]
	v_pk_mul_f32 v[168:169], v[126:127], v[126:127]
	v_cvt_pk_bf16_f32 v114, v126, v127
	v_cvt_pk_bf16_f32 v115, v128, v129
	v_cvt_pk_bf16_f32 v116, v122, v123
	v_cvt_pk_bf16_f32 v117, v124, v125
	v_pk_mul_f32 v[170:171], v[128:129], v[128:129]
	global_store_dwordx4 v[156:157], v[114:117], off
	v_pk_mul_f32 v[172:173], v[122:123], v[122:123]
	v_pk_mul_f32 v[174:175], v[124:125], v[124:125]
	v_add_f32_e32 v114, v168, v169
	v_add_f32_e32 v114, v170, v114
	v_add_f32_e32 v114, v171, v114
	v_add_f32_e32 v114, v172, v114
	v_add_f32_e32 v114, v173, v114
	v_pk_add_f32 v[118:119], v[118:119], v[176:177]
	v_add_f32_e32 v114, v174, v114
	v_pk_mul_f32 v[122:123], v[118:119], v[118:119]
	v_add_f32_e32 v114, v175, v114
	v_add_f32_e32 v114, v122, v114
	v_pk_mul_f32 v[124:125], v[120:121], v[120:121]
	v_add_f32_e32 v114, v123, v114
	v_add_f32_e32 v114, v124, v114
	v_pk_mul_f32 v[126:127], v[164:165], v[164:165]
	v_add_f32_e32 v114, v125, v114
	v_add_f32_e32 v114, v126, v114
	v_pk_mul_f32 v[128:129], v[166:167], v[166:167]
	v_add_f32_e32 v114, v127, v114
	v_add_f32_e32 v114, v128, v114
	v_add_f32_e32 v114, v129, v114
	v_xor_b32_e32 v115, 0x80000000, v114
	s_nop 1
	v_permlane16_swap_b32_e32 v114, v115
	v_cvt_pk_bf16_f32 v118, v118, v119
	v_add_f32_e32 v115, v114, v115
	v_and_b32_e32 v114, 0x7fffffff, v115
	v_or_b32_e32 v115, 0x80000000, v115
	v_cvt_pk_bf16_f32 v119, v120, v121
	v_cvt_pk_bf16_f32 v120, v164, v165
	v_cvt_pk_bf16_f32 v121, v166, v167
	v_permlane32_swap_b32_e32 v114, v115
	global_store_dwordx4 v[156:157], v[118:121], off offset:256
	s_and_saveexec_b64 s[12:13], s[2:3]
	v_readlane_b32 s16, v254, 35
	s_cbranch_execz .LBB0_1240
	v_lshlrev_b64 v[116:117], 6, v[154:155]
	v_lshl_add_u64 v[116:117], s[10:11], 0, v[116:117]
	v_lshl_add_u64 v[116:117], s[8:9], 2, v[116:117]
	s_lshl_b32 s72, s16, 2
	v_add_f32_e32 v114, v114, v115
	v_lshl_add_u64 v[116:117], v[116:117], 0, s[72:73]
	v_and_b32_e32 v114, 0x7fffffff, v114
	global_store_dword v[116:117], v114, off
; __device__ __forceinline__ u32x4 pack8(const float (&v)[8]) { u32x4 w; w.x = pk2(v[0], v[1]); w.y = pk2(v[2], v[3]); w.z = pk2(v[4], v[5]); w.w = pk2(v[6], v[7]); return w; }
; __device__ __forceinline__ float xsum16p(float x) { const unsigned u = __builtin_bit_cast(unsigned, x); const auto r = __builtin_amdgcn_permlane16_swap(u, u ^ 0x80000000u, false, false); unsigned r0 = r[0], r1 = r[1]; asm("" : "+v"(r0), "+v"(r1)); return fabsf(__builtin_bit_cast(float, r0) + __builtin_bit_cast(float, r1)); }
; __device__ __forceinline__ float xsum32p(float x) { const unsigned u = __builtin_bit_cast(unsigned, x); const auto r = __builtin_amdgcn_permlane32_swap(u, u ^ 0x80000000u, false, false); unsigned r0 = r[0], r1 = r[1]; asm("" : "+v"(r0), "+v"(r1)); return fabsf(__builtin_bit_cast(float, r0) + __builtin_bit_cast(float, r1)); }
;     __device__ __forceinline__ void row_group(Acc& acc, const int ai, const int m, const float (&xo0)[8], const float (&xo1)[8], bf16_t* xb0, const int row0, const int pn, const int wc, const int fq) const {
;         float ssq = 0.f;
; #pragma unroll
;         for (int bj = 0; bj < 2; ++bj) {
;             float v[8];
; #pragma unroll
;             for (int e = 0; e < 4; ++e) { const float a0 = bj ? xo1[e] : xo0[e], a1 = bj ? xo1[4 + e] : xo0[4 + e]; v[e] = dry ? a0 : a0 + acc[ai][bj][m][0][e]; v[4 + e] = dry ? a1 : a1 + acc[ai][bj][m][1][e]; }
; #pragma unroll
;             for (int e = 0; e < 8; ++e) ssq += v[e] * v[e];
;             gst<u32x4>(xb0 + (size_t)(ai * HALF + m * 16) * DM + bj * HALF, pack8(v));
;         }
;         ssq = xsum32p(xsum16p(ssq));
;         if (fq == 0) gst<float>(ss_next + (size_t)(row0 + ai * HALF + m * 16) * 16 + pn * 4 + wc, ssq);
;     }
.LBB0_1240:
	s_or_b64 exec, exec, s[12:13]
	s_waitcnt vmcnt(15)
	v_lshlrev_b32_e32 v118, 16, v150
	v_and_b32_e32 v119, 0xffff0000, v150
	v_pk_add_f32 v[110:111], v[110:111], v[118:119]
	v_lshlrev_b32_e32 v118, 16, v152
	v_and_b32_e32 v119, 0xffff0000, v152
	v_pk_add_f32 v[118:119], v[106:107], v[118:119]
	v_lshlrev_b32_e32 v106, 16, v151
	v_and_b32_e32 v107, 0xffff0000, v151
	v_pk_add_f32 v[112:113], v[112:113], v[106:107]
	v_lshlrev_b32_e32 v106, 16, v153
	v_and_b32_e32 v107, 0xffff0000, v153
	s_mov_b64 s[12:13], 0x8000
	v_pk_add_f32 v[120:121], v[108:109], v[106:107]
	v_lshl_add_u64 v[114:115], v[156:157], 0, s[12:13]
	v_pk_mul_f32 v[122:123], v[110:111], v[110:111]
	v_cvt_pk_bf16_f32 v106, v110, v111
	v_cvt_pk_bf16_f32 v107, v112, v113
	v_cvt_pk_bf16_f32 v108, v118, v119
	v_cvt_pk_bf16_f32 v109, v120, v121
	v_pk_mul_f32 v[124:125], v[112:113], v[112:113]
	global_store_dwordx4 v[114:115], v[106:109], off
	v_add_f32_e32 v114, v122, v123
	v_add_f32_e32 v114, v124, v114
	v_pk_mul_f32 v[126:127], v[118:119], v[118:119]
	s_waitcnt vmcnt(15)
	v_lshlrev_b32_e32 v106, 16, v146
	v_and_b32_e32 v107, 0xffff0000, v146
	v_add_f32_e32 v114, v125, v114
	v_pk_add_f32 v[102:103], v[102:103], v[106:107]
	v_lshlrev_b32_e32 v106, 16, v148
	v_and_b32_e32 v107, 0xffff0000, v148
	v_add_f32_e32 v114, v126, v114
	v_pk_mul_f32 v[128:129], v[120:121], v[120:121]
	v_pk_add_f32 v[106:107], v[98:99], v[106:107]
	v_lshlrev_b32_e32 v98, 16, v147
	v_and_b32_e32 v99, 0xffff0000, v147
	v_add_f32_e32 v114, v127, v114
	v_pk_add_f32 v[104:105], v[104:105], v[98:99]
	v_lshlrev_b32_e32 v98, 16, v149
	v_and_b32_e32 v99, 0xffff0000, v149
	v_add_f32_e32 v114, v128, v114
	v_pk_add_f32 v[108:109], v[100:101], v[98:99]
	v_pk_mul_f32 v[98:99], v[102:103], v[102:103]
	v_add_f32_e32 v114, v129, v114
	v_add_f32_e32 v98, v98, v114
	v_pk_mul_f32 v[100:101], v[104:105], v[104:105]
	v_add_f32_e32 v98, v99, v98
	v_add_f32_e32 v98, v100, v98
	v_pk_mul_f32 v[110:111], v[106:107], v[106:107]
	v_add_f32_e32 v98, v101, v98
	v_add_f32_e32 v98, v110, v98
	v_pk_mul_f32 v[112:113], v[108:109], v[108:109]
	v_add_f32_e32 v98, v111, v98
	s_mov_b64 s[12:13], 0x8100
	v_add_f32_e32 v98, v112, v98
	v_lshl_add_u64 v[116:117], v[156:157], 0, s[12:13]
	v_add_f32_e32 v110, v113, v98
	v_cvt_pk_bf16_f32 v98, v102, v103
	v_cvt_pk_bf16_f32 v99, v104, v105
	v_cvt_pk_bf16_f32 v100, v106, v107
	v_cvt_pk_bf16_f32 v101, v108, v109
	global_store_dwordx4 v[116:117], v[98:101], off
	s_nop 1
	v_xor_b32_e32 v98, 0x80000000, v110
	s_nop 1
	v_permlane16_swap_b32_e32 v110, v98
	s_nop 0
	v_add_f32_e32 v99, v110, v98
	v_and_b32_e32 v98, 0x7fffffff, v99
	v_or_b32_e32 v99, 0x80000000, v99
	s_nop 1
	v_permlane32_swap_b32_e32 v98, v99
	s_and_saveexec_b64 s[12:13], s[2:3]
	s_cbranch_execz .LBB0_1242
	v_add_f32_e32 v98, v98, v99
	v_and_b32_e32 v100, 0x7fffffff, v98
	v_or_b32_e32 v98, 16, v154
	v_ashrrev_i32_e32 v99, 31, v98
	v_lshlrev_b64 v[98:99], 6, v[98:99]
	v_lshl_add_u64 v[98:99], s[10:11], 0, v[98:99]
	v_lshl_add_u64 v[98:99], s[8:9], 2, v[98:99]
	s_lshl_b32 s72, s16, 2
	v_lshl_add_u64 v[98:99], v[98:99], 0, s[72:73]
	global_store_dword v[98:99], v100, off
.LBB0_1242:
	s_or_b64 exec, exec, s[12:13]
	s_waitcnt vmcnt(15)
	v_lshlrev_b32_e32 v102, 16, v142
	v_and_b32_e32 v103, 0xffff0000, v142
	v_pk_add_f32 v[94:95], v[94:95], v[102:103]
	v_lshlrev_b32_e32 v102, 16, v144
	v_and_b32_e32 v103, 0xffff0000, v144
	v_pk_add_f32 v[102:103], v[90:91], v[102:103]
	v_lshlrev_b32_e32 v90, 16, v143
	v_and_b32_e32 v91, 0xffff0000, v143
	v_pk_add_f32 v[96:97], v[96:97], v[90:91]
	v_lshlrev_b32_e32 v90, 16, v145
	v_and_b32_e32 v91, 0xffff0000, v145
	s_mov_b64 s[12:13], 0x10000
	v_pk_add_f32 v[104:105], v[92:93], v[90:91]
	v_lshl_add_u64 v[98:99], v[156:157], 0, s[12:13]
	v_pk_mul_f32 v[106:107], v[94:95], v[94:95]
	v_cvt_pk_bf16_f32 v90, v94, v95
	v_cvt_pk_bf16_f32 v91, v96, v97
	v_cvt_pk_bf16_f32 v92, v102, v103
	v_cvt_pk_bf16_f32 v93, v104, v105
	v_pk_mul_f32 v[108:109], v[96:97], v[96:97]
	global_store_dwordx4 v[98:99], v[90:93], off
	v_add_f32_e32 v98, v106, v107
	v_add_f32_e32 v98, v108, v98
	v_pk_mul_f32 v[110:111], v[102:103], v[102:103]
	s_waitcnt vmcnt(15)
	v_lshlrev_b32_e32 v90, 16, v138
	v_and_b32_e32 v91, 0xffff0000, v138
	v_add_f32_e32 v98, v109, v98
	v_pk_add_f32 v[86:87], v[86:87], v[90:91]
	v_lshlrev_b32_e32 v90, 16, v140
	v_and_b32_e32 v91, 0xffff0000, v140
	v_add_f32_e32 v98, v110, v98
	v_pk_mul_f32 v[112:113], v[104:105], v[104:105]
	v_pk_add_f32 v[90:91], v[82:83], v[90:91]
	v_lshlrev_b32_e32 v82, 16, v139
	v_and_b32_e32 v83, 0xffff0000, v139
	v_add_f32_e32 v98, v111, v98
	v_pk_add_f32 v[88:89], v[88:89], v[82:83]
	v_lshlrev_b32_e32 v82, 16, v141
	v_and_b32_e32 v83, 0xffff0000, v141
	v_add_f32_e32 v98, v112, v98
	v_pk_add_f32 v[92:93], v[84:85], v[82:83]
	v_pk_mul_f32 v[82:83], v[86:87], v[86:87]
	v_add_f32_e32 v98, v113, v98
	v_add_f32_e32 v82, v82, v98
	v_pk_mul_f32 v[84:85], v[88:89], v[88:89]
	v_add_f32_e32 v82, v83, v82
	v_add_f32_e32 v82, v84, v82
	v_pk_mul_f32 v[94:95], v[90:91], v[90:91]
	v_add_f32_e32 v82, v85, v82
	v_add_f32_e32 v82, v94, v82
	v_pk_mul_f32 v[96:97], v[92:93], v[92:93]
	v_add_f32_e32 v82, v95, v82
	s_mov_b64 s[12:13], 0x10100
	v_add_f32_e32 v82, v96, v82
	v_lshl_add_u64 v[100:101], v[156:157], 0, s[12:13]
	v_add_f32_e32 v94, v97, v82
	v_cvt_pk_bf16_f32 v82, v86, v87
	v_cvt_pk_bf16_f32 v83, v88, v89
	v_cvt_pk_bf16_f32 v84, v90, v91
	v_cvt_pk_bf16_f32 v85, v92, v93
	global_store_dwordx4 v[100:101], v[82:85], off
	s_nop 1
	v_xor_b32_e32 v82, 0x80000000, v94
	s_nop 1
	v_permlane16_swap_b32_e32 v94, v82
	s_nop 0
	v_add_f32_e32 v83, v94, v82
	v_and_b32_e32 v82, 0x7fffffff, v83
	v_or_b32_e32 v83, 0x80000000, v83
	s_nop 1
	v_permlane32_swap_b32_e32 v82, v83
	s_and_saveexec_b64 s[12:13], s[2:3]
	s_cbranch_execz .LBB0_1244
	v_add_f32_e32 v82, v82, v83
	v_and_b32_e32 v84, 0x7fffffff, v82
	v_or_b32_e32 v82, 32, v154
	v_ashrrev_i32_e32 v83, 31, v82
	v_lshlrev_b64 v[82:83], 6, v[82:83]
	v_lshl_add_u64 v[82:83], s[10:11], 0, v[82:83]
	v_lshl_add_u64 v[82:83], s[8:9], 2, v[82:83]
	s_lshl_b32 s72, s16, 2
	v_lshl_add_u64 v[82:83], v[82:83], 0, s[72:73]
	global_store_dword v[82:83], v84, off
; #define LAS __attribute__((address_space(3)))
; __device__ __forceinline__ void unpack8(const u32x4 w, float (&v)[8]) { v[0] = bflo(w.x); v[1] = bfhi(w.x); v[2] = bflo(w.y); v[3] = bfhi(w.y); v[4] = bflo(w.z); v[5] = bfhi(w.z); v[6] = bflo(w.w); v[7] = bfhi(w.w); }
;     __device__ __forceinline__ bool operator()(Acc& acc, const Unit& u, int wr, int wc, int fr, int fq, const LAS float*) const {
;         const int row0 = u.pm * BM + wr * 64 + fr, col0 = u.pn * BM + wc * 32 + 8 * fq;
;         bf16_t* xb0 = XB + (size_t)row0 * DM + col0; const float* xi0 = Xin + (size_t)row0 * DM + col0;
; #pragma unroll
;         for (int ai = 0; ai < 2; ++ai) {
;             u32x4 xv[4][2];
; #pragma unroll
;             for (int m = 0; m < 4; ++m)
; #pragma unroll
;                 for (int bj = 0; bj < 2; ++bj) xv[m][bj] = gld<u32x4>(xb0 + (size_t)(ai * HALF + m * 16) * DM + bj * HALF);
; #pragma unroll
;             for (int m = 0; m < 4; ++m) {
;                 float x0[8], x1[8]; unpack8(xv[m][0], x0); unpack8(xv[m][1], x1);
;                 row_group(acc, ai, m, x0, x1, xb0, row0, u.pn, wc, fq);
.LBB0_1244:
	s_or_b64 exec, exec, s[12:13]
	s_waitcnt vmcnt(15)
	v_lshlrev_b32_e32 v86, 16, v134
	v_and_b32_e32 v87, 0xffff0000, v134
	v_pk_add_f32 v[78:79], v[78:79], v[86:87]
	v_lshlrev_b32_e32 v86, 16, v136
	v_and_b32_e32 v87, 0xffff0000, v136
	v_pk_add_f32 v[86:87], v[74:75], v[86:87]
	v_lshlrev_b32_e32 v74, 16, v135
	v_and_b32_e32 v75, 0xffff0000, v135
	v_pk_add_f32 v[80:81], v[80:81], v[74:75]
	v_lshlrev_b32_e32 v74, 16, v137
	v_and_b32_e32 v75, 0xffff0000, v137
	s_mov_b64 s[12:13], 0x18000
	v_pk_add_f32 v[88:89], v[76:77], v[74:75]
	v_lshl_add_u64 v[82:83], v[156:157], 0, s[12:13]
	v_pk_mul_f32 v[90:91], v[78:79], v[78:79]
	v_cvt_pk_bf16_f32 v74, v78, v79
	v_cvt_pk_bf16_f32 v75, v80, v81
	v_cvt_pk_bf16_f32 v76, v86, v87
	v_cvt_pk_bf16_f32 v77, v88, v89
	v_pk_mul_f32 v[92:93], v[80:81], v[80:81]
	global_store_dwordx4 v[82:83], v[74:77], off
	v_add_f32_e32 v82, v90, v91
	v_add_f32_e32 v82, v92, v82
	v_pk_mul_f32 v[94:95], v[86:87], v[86:87]
	s_waitcnt vmcnt(15)
	v_lshlrev_b32_e32 v74, 16, v130
	v_and_b32_e32 v75, 0xffff0000, v130
	v_add_f32_e32 v82, v93, v82
	v_pk_add_f32 v[70:71], v[70:71], v[74:75]
	v_lshlrev_b32_e32 v74, 16, v132
	v_and_b32_e32 v75, 0xffff0000, v132
	v_add_f32_e32 v82, v94, v82
	v_pk_mul_f32 v[96:97], v[88:89], v[88:89]
	v_pk_add_f32 v[74:75], v[66:67], v[74:75]
	v_lshlrev_b32_e32 v66, 16, v131
	v_and_b32_e32 v67, 0xffff0000, v131
	v_add_f32_e32 v82, v95, v82
	v_pk_add_f32 v[72:73], v[72:73], v[66:67]
	v_lshlrev_b32_e32 v66, 16, v133
	v_and_b32_e32 v67, 0xffff0000, v133
	v_add_f32_e32 v82, v96, v82
	v_pk_add_f32 v[76:77], v[68:69], v[66:67]
	v_pk_mul_f32 v[66:67], v[70:71], v[70:71]
	v_add_f32_e32 v82, v97, v82
	v_add_f32_e32 v66, v66, v82
	v_pk_mul_f32 v[68:69], v[72:73], v[72:73]
	v_add_f32_e32 v66, v67, v66
	v_add_f32_e32 v66, v68, v66
	v_pk_mul_f32 v[78:79], v[74:75], v[74:75]
	v_add_f32_e32 v66, v69, v66
	v_add_f32_e32 v66, v78, v66
	v_pk_mul_f32 v[80:81], v[76:77], v[76:77]
	v_add_f32_e32 v66, v79, v66
	s_mov_b64 s[12:13], 0x18100
	v_add_f32_e32 v66, v80, v66
	v_lshl_add_u64 v[84:85], v[156:157], 0, s[12:13]
	v_add_f32_e32 v78, v81, v66
	v_cvt_pk_bf16_f32 v66, v70, v71
	v_cvt_pk_bf16_f32 v67, v72, v73
	v_cvt_pk_bf16_f32 v68, v74, v75
	v_cvt_pk_bf16_f32 v69, v76, v77
	global_store_dwordx4 v[84:85], v[66:69], off
	s_nop 1
	v_xor_b32_e32 v66, 0x80000000, v78
	s_nop 1
	v_permlane16_swap_b32_e32 v78, v66
	s_nop 0
	v_add_f32_e32 v67, v78, v66
	v_and_b32_e32 v66, 0x7fffffff, v67
	v_or_b32_e32 v67, 0x80000000, v67
	s_nop 1
	v_permlane32_swap_b32_e32 v66, v67
	s_and_saveexec_b64 s[12:13], s[2:3]
	s_cbranch_execz .LBB0_1246
	v_add_f32_e32 v66, v66, v67
	v_and_b32_e32 v68, 0x7fffffff, v66
	v_or_b32_e32 v66, 48, v154
	v_ashrrev_i32_e32 v67, 31, v66
	v_lshlrev_b64 v[66:67], 6, v[66:67]
	v_lshl_add_u64 v[66:67], s[10:11], 0, v[66:67]
	v_lshl_add_u64 v[66:67], s[8:9], 2, v[66:67]
	s_lshl_b32 s72, s16, 2
	v_lshl_add_u64 v[66:67], v[66:67], 0, s[72:73]
	global_store_dword v[66:67], v68, off
.LBB0_1246:
	s_or_b64 exec, exec, s[12:13]
	s_waitcnt vmcnt(8)
	v_add_co_u32_e32 v90, vcc, 0x40000, v156
	s_nop 1
	v_addc_co_u32_e32 v91, vcc, 0, v157, vcc
	v_mov_b64_e32 v[92:93], v[180:181]
	v_mov_b64_e32 v[94:95], v[182:183]
	v_mov_b64_e32 v[96:97], v[184:185]
	v_mov_b64_e32 v[98:99], v[186:187]
	v_add_co_u32_e32 v66, vcc, 0x48000, v156
	v_lshlrev_b32_e32 v100, 16, v92
	v_addc_co_u32_e32 v67, vcc, 0, v157, vcc
	v_mov_b64_e32 v[86:87], v[188:189]
	v_mov_b64_e32 v[88:89], v[190:191]
	v_mov_b64_e32 v[82:83], v[192:193]
	v_mov_b64_e32 v[84:85], v[194:195]
	v_add_co_u32_e32 v66, vcc, 0x50000, v156
	v_and_b32_e32 v101, 0xffff0000, v92
	s_nop 0
	v_addc_co_u32_e32 v67, vcc, 0, v157, vcc
	v_mov_b64_e32 v[78:79], v[200:201]
	v_mov_b64_e32 v[80:81], v[202:203]
	v_mov_b64_e32 v[74:75], v[206:207]
	v_mov_b64_e32 v[76:77], v[208:209]
	v_add_co_u32_e32 v66, vcc, 0x58000, v156
	v_pk_add_f32 v[62:63], v[62:63], v[100:101]
	s_nop 0
	v_addc_co_u32_e32 v67, vcc, 0, v157, vcc
	v_mov_b64_e32 v[70:71], v[210:211]
	v_mov_b64_e32 v[72:73], v[212:213]
	s_nop 0
	v_mov_b64_e32 v[66:67], v[214:215]
	v_mov_b64_e32 v[68:69], v[216:217]
	v_lshlrev_b32_e32 v100, 16, v94
	v_and_b32_e32 v101, 0xffff0000, v94
	v_pk_add_f32 v[100:101], v[58:59], v[100:101]
	v_lshlrev_b32_e32 v58, 16, v93
	v_and_b32_e32 v59, 0xffff0000, v93
	v_pk_add_f32 v[64:65], v[64:65], v[58:59]
	v_lshlrev_b32_e32 v58, 16, v95
	v_and_b32_e32 v59, 0xffff0000, v95
	v_pk_add_f32 v[92:93], v[60:61], v[58:59]
	v_pk_mul_f32 v[94:95], v[62:63], v[62:63]
	v_pk_mul_f32 v[102:103], v[64:65], v[64:65]
	v_pk_mul_f32 v[106:107], v[92:93], v[92:93]
	v_cvt_pk_bf16_f32 v61, v92, v93
	v_add_f32_e32 v92, v94, v95
	v_cvt_pk_bf16_f32 v58, v62, v63
	v_cvt_pk_bf16_f32 v59, v64, v65
	v_cvt_pk_bf16_f32 v60, v100, v101
	v_add_f32_e32 v92, v102, v92
	v_pk_mul_f32 v[104:105], v[100:101], v[100:101]
	global_store_dwordx4 v[90:91], v[58:61], off
	v_add_f32_e32 v92, v103, v92
	v_add_f32_e32 v92, v104, v92
	v_lshlrev_b32_e32 v58, 16, v96
	v_and_b32_e32 v59, 0xffff0000, v96
	v_pk_add_f32 v[54:55], v[54:55], v[58:59]
	v_lshlrev_b32_e32 v58, 16, v98
	v_and_b32_e32 v59, 0xffff0000, v98
	v_pk_add_f32 v[58:59], v[50:51], v[58:59]
	v_lshlrev_b32_e32 v50, 16, v97
	v_and_b32_e32 v51, 0xffff0000, v97
	v_add_f32_e32 v92, v105, v92
	v_pk_add_f32 v[56:57], v[56:57], v[50:51]
	v_lshlrev_b32_e32 v50, 16, v99
	v_and_b32_e32 v51, 0xffff0000, v99
	v_add_f32_e32 v92, v106, v92
	v_pk_add_f32 v[60:61], v[52:53], v[50:51]
	v_pk_mul_f32 v[50:51], v[54:55], v[54:55]
	v_add_f32_e32 v92, v107, v92
	v_add_f32_e32 v50, v50, v92
	v_pk_mul_f32 v[52:53], v[56:57], v[56:57]
	v_add_f32_e32 v50, v51, v50
	v_add_f32_e32 v50, v52, v50
	v_pk_mul_f32 v[62:63], v[58:59], v[58:59]
	v_add_f32_e32 v50, v53, v50
	v_add_f32_e32 v50, v62, v50
	v_pk_mul_f32 v[64:65], v[60:61], v[60:61]
	v_add_f32_e32 v50, v63, v50
	v_add_f32_e32 v50, v64, v50
	v_add_f32_e32 v62, v65, v50
	v_cvt_pk_bf16_f32 v50, v54, v55
	v_cvt_pk_bf16_f32 v51, v56, v57
	v_cvt_pk_bf16_f32 v52, v58, v59
	v_cvt_pk_bf16_f32 v53, v60, v61
	global_store_dwordx4 v[90:91], v[50:53], off offset:256
	s_nop 1
	v_xor_b32_e32 v50, 0x80000000, v62
	s_nop 1
	v_permlane16_swap_b32_e32 v62, v50
	s_nop 0
	v_add_f32_e32 v51, v62, v50
	v_and_b32_e32 v50, 0x7fffffff, v51
	v_or_b32_e32 v51, 0x80000000, v51
	s_nop 1
	v_permlane32_swap_b32_e32 v50, v51
	s_and_saveexec_b64 s[12:13], s[2:3]
	s_cbranch_execz .LBB0_1248
	v_add_f32_e32 v50, v50, v51
	v_and_b32_e32 v52, 0x7fffffff, v50
	v_add_u32_e32 v50, 0x80, v154
	v_ashrrev_i32_e32 v51, 31, v50
	v_lshlrev_b64 v[50:51], 6, v[50:51]
	v_lshl_add_u64 v[50:51], s[10:11], 0, v[50:51]
	v_lshl_add_u64 v[50:51], s[8:9], 2, v[50:51]
	s_lshl_b32 s72, s16, 2
	v_lshl_add_u64 v[50:51], v[50:51], 0, s[72:73]
	global_store_dword v[50:51], v52, off
; __device__ __forceinline__ u32x4 pack8(const float (&v)[8]) { u32x4 w; w.x = pk2(v[0], v[1]); w.y = pk2(v[2], v[3]); w.z = pk2(v[4], v[5]); w.w = pk2(v[6], v[7]); return w; }
; __device__ __forceinline__ float xsum16p(float x) { const unsigned u = __builtin_bit_cast(unsigned, x); const auto r = __builtin_amdgcn_permlane16_swap(u, u ^ 0x80000000u, false, false); unsigned r0 = r[0], r1 = r[1]; asm("" : "+v"(r0), "+v"(r1)); return fabsf(__builtin_bit_cast(float, r0) + __builtin_bit_cast(float, r1)); }
; __device__ __forceinline__ float xsum32p(float x) { const unsigned u = __builtin_bit_cast(unsigned, x); const auto r = __builtin_amdgcn_permlane32_swap(u, u ^ 0x80000000u, false, false); unsigned r0 = r[0], r1 = r[1]; asm("" : "+v"(r0), "+v"(r1)); return fabsf(__builtin_bit_cast(float, r0) + __builtin_bit_cast(float, r1)); }
;     __device__ __forceinline__ void row_group(Acc& acc, const int ai, const int m, const float (&xo0)[8], const float (&xo1)[8], bf16_t* xb0, const int row0, const int pn, const int wc, const int fq) const {
;         float ssq = 0.f;
; #pragma unroll
;         for (int bj = 0; bj < 2; ++bj) {
;             float v[8];
; #pragma unroll
;             for (int e = 0; e < 4; ++e) { const float a0 = bj ? xo1[e] : xo0[e], a1 = bj ? xo1[4 + e] : xo0[4 + e]; v[e] = dry ? a0 : a0 + acc[ai][bj][m][0][e]; v[4 + e] = dry ? a1 : a1 + acc[ai][bj][m][1][e]; }
; #pragma unroll
;             for (int e = 0; e < 8; ++e) ssq += v[e] * v[e];
;             gst<u32x4>(xb0 + (size_t)(ai * HALF + m * 16) * DM + bj * HALF, pack8(v));
;         }
;         ssq = xsum32p(xsum16p(ssq));
;         if (fq == 0) gst<float>(ss_next + (size_t)(row0 + ai * HALF + m * 16) * 16 + pn * 4 + wc, ssq);
;     }
.LBB0_1248:
	s_or_b64 exec, exec, s[12:13]
	v_lshlrev_b32_e32 v54, 16, v86
	v_and_b32_e32 v55, 0xffff0000, v86
	v_pk_add_f32 v[46:47], v[46:47], v[54:55]
	v_lshlrev_b32_e32 v54, 16, v88
	v_and_b32_e32 v55, 0xffff0000, v88
	v_pk_add_f32 v[54:55], v[42:43], v[54:55]
	v_lshlrev_b32_e32 v42, 16, v87
	v_and_b32_e32 v43, 0xffff0000, v87
	v_pk_add_f32 v[48:49], v[48:49], v[42:43]
	v_lshlrev_b32_e32 v42, 16, v89
	v_and_b32_e32 v43, 0xffff0000, v89
	s_mov_b64 s[12:13], 0x48000
	v_pk_add_f32 v[56:57], v[44:45], v[42:43]
	v_lshl_add_u64 v[50:51], v[156:157], 0, s[12:13]
	v_pk_mul_f32 v[58:59], v[46:47], v[46:47]
	v_cvt_pk_bf16_f32 v42, v46, v47
	v_cvt_pk_bf16_f32 v43, v48, v49
	v_cvt_pk_bf16_f32 v44, v54, v55
	v_cvt_pk_bf16_f32 v45, v56, v57
	v_pk_mul_f32 v[60:61], v[48:49], v[48:49]
	global_store_dwordx4 v[50:51], v[42:45], off
	v_add_f32_e32 v50, v58, v59
	v_add_f32_e32 v50, v60, v50
	v_pk_mul_f32 v[62:63], v[54:55], v[54:55]
	v_lshlrev_b32_e32 v42, 16, v82
	v_and_b32_e32 v43, 0xffff0000, v82
	v_add_f32_e32 v50, v61, v50
	v_pk_add_f32 v[38:39], v[38:39], v[42:43]
	v_lshlrev_b32_e32 v42, 16, v84
	v_and_b32_e32 v43, 0xffff0000, v84
	v_add_f32_e32 v50, v62, v50
	v_pk_mul_f32 v[64:65], v[56:57], v[56:57]
	v_pk_add_f32 v[42:43], v[34:35], v[42:43]
	v_lshlrev_b32_e32 v34, 16, v83
	v_and_b32_e32 v35, 0xffff0000, v83
	v_add_f32_e32 v50, v63, v50
	v_pk_add_f32 v[40:41], v[40:41], v[34:35]
	v_lshlrev_b32_e32 v34, 16, v85
	v_and_b32_e32 v35, 0xffff0000, v85
	v_add_f32_e32 v50, v64, v50
	v_pk_add_f32 v[44:45], v[36:37], v[34:35]
	v_pk_mul_f32 v[34:35], v[38:39], v[38:39]
	v_add_f32_e32 v50, v65, v50
	v_add_f32_e32 v34, v34, v50
	v_pk_mul_f32 v[36:37], v[40:41], v[40:41]
	v_add_f32_e32 v34, v35, v34
	v_add_f32_e32 v34, v36, v34
	v_pk_mul_f32 v[46:47], v[42:43], v[42:43]
	v_add_f32_e32 v34, v37, v34
	v_add_f32_e32 v34, v46, v34
	v_pk_mul_f32 v[48:49], v[44:45], v[44:45]
	v_add_f32_e32 v34, v47, v34
	s_mov_b64 s[12:13], 0x48100
	v_add_f32_e32 v34, v48, v34
	v_lshl_add_u64 v[52:53], v[156:157], 0, s[12:13]
	v_add_f32_e32 v46, v49, v34
	v_cvt_pk_bf16_f32 v34, v38, v39
	v_cvt_pk_bf16_f32 v35, v40, v41
	v_cvt_pk_bf16_f32 v36, v42, v43
	v_cvt_pk_bf16_f32 v37, v44, v45
	global_store_dwordx4 v[52:53], v[34:37], off
	s_nop 1
	v_xor_b32_e32 v34, 0x80000000, v46
	s_nop 1
	v_permlane16_swap_b32_e32 v46, v34
	s_nop 0
	v_add_f32_e32 v35, v46, v34
	v_and_b32_e32 v34, 0x7fffffff, v35
	v_or_b32_e32 v35, 0x80000000, v35
	s_nop 1
	v_permlane32_swap_b32_e32 v34, v35
	s_and_saveexec_b64 s[12:13], s[2:3]
	s_cbranch_execz .LBB0_1250
	v_add_f32_e32 v34, v34, v35
	v_and_b32_e32 v36, 0x7fffffff, v34
	v_add_u32_e32 v34, 0x90, v154
	v_ashrrev_i32_e32 v35, 31, v34
	v_lshlrev_b64 v[34:35], 6, v[34:35]
	v_lshl_add_u64 v[34:35], s[10:11], 0, v[34:35]
	v_lshl_add_u64 v[34:35], s[8:9], 2, v[34:35]
	s_lshl_b32 s72, s16, 2
	v_lshl_add_u64 v[34:35], v[34:35], 0, s[72:73]
	global_store_dword v[34:35], v36, off
; __device__ __forceinline__ u32x4 pack8(const float (&v)[8]) { u32x4 w; w.x = pk2(v[0], v[1]); w.y = pk2(v[2], v[3]); w.z = pk2(v[4], v[5]); w.w = pk2(v[6], v[7]); return w; }
; __device__ __forceinline__ float xsum16p(float x) { const unsigned u = __builtin_bit_cast(unsigned, x); const auto r = __builtin_amdgcn_permlane16_swap(u, u ^ 0x80000000u, false, false); unsigned r0 = r[0], r1 = r[1]; asm("" : "+v"(r0), "+v"(r1)); return fabsf(__builtin_bit_cast(float, r0) + __builtin_bit_cast(float, r1)); }
; __device__ __forceinline__ float xsum32p(float x) { const unsigned u = __builtin_bit_cast(unsigned, x); const auto r = __builtin_amdgcn_permlane32_swap(u, u ^ 0x80000000u, false, false); unsigned r0 = r[0], r1 = r[1]; asm("" : "+v"(r0), "+v"(r1)); return fabsf(__builtin_bit_cast(float, r0) + __builtin_bit_cast(float, r1)); }
;     __device__ __forceinline__ void row_group(Acc& acc, const int ai, const int m, const float (&xo0)[8], const float (&xo1)[8], bf16_t* xb0, const int row0, const int pn, const int wc, const int fq) const {
;         float ssq = 0.f;
; #pragma unroll
;         for (int bj = 0; bj < 2; ++bj) {
;             float v[8];
; #pragma unroll
;             for (int e = 0; e < 4; ++e) { const float a0 = bj ? xo1[e] : xo0[e], a1 = bj ? xo1[4 + e] : xo0[4 + e]; v[e] = dry ? a0 : a0 + acc[ai][bj][m][0][e]; v[4 + e] = dry ? a1 : a1 + acc[ai][bj][m][1][e]; }
; #pragma unroll
;             for (int e = 0; e < 8; ++e) ssq += v[e] * v[e];
;             gst<u32x4>(xb0 + (size_t)(ai * HALF + m * 16) * DM + bj * HALF, pack8(v));
;         }
;         ssq = xsum32p(xsum16p(ssq));
;         if (fq == 0) gst<float>(ss_next + (size_t)(row0 + ai * HALF + m * 16) * 16 + pn * 4 + wc, ssq);
;     }
.LBB0_1250:
	s_or_b64 exec, exec, s[12:13]
	v_lshlrev_b32_e32 v38, 16, v78
	v_and_b32_e32 v39, 0xffff0000, v78
	v_pk_add_f32 v[30:31], v[30:31], v[38:39]
	v_lshlrev_b32_e32 v38, 16, v80
	v_and_b32_e32 v39, 0xffff0000, v80
	v_pk_add_f32 v[38:39], v[26:27], v[38:39]
	v_lshlrev_b32_e32 v26, 16, v79
	v_and_b32_e32 v27, 0xffff0000, v79
	v_pk_add_f32 v[32:33], v[32:33], v[26:27]
	v_lshlrev_b32_e32 v26, 16, v81
	v_and_b32_e32 v27, 0xffff0000, v81
	s_mov_b64 s[12:13], 0x50000
	v_pk_add_f32 v[40:41], v[28:29], v[26:27]
	v_lshl_add_u64 v[34:35], v[156:157], 0, s[12:13]
	v_pk_mul_f32 v[42:43], v[30:31], v[30:31]
	v_cvt_pk_bf16_f32 v26, v30, v31
	v_cvt_pk_bf16_f32 v27, v32, v33
	v_cvt_pk_bf16_f32 v28, v38, v39
	v_cvt_pk_bf16_f32 v29, v40, v41
	v_pk_mul_f32 v[44:45], v[32:33], v[32:33]
	global_store_dwordx4 v[34:35], v[26:29], off
	v_add_f32_e32 v34, v42, v43
	v_add_f32_e32 v34, v44, v34
	v_pk_mul_f32 v[46:47], v[38:39], v[38:39]
	v_lshlrev_b32_e32 v26, 16, v74
	v_and_b32_e32 v27, 0xffff0000, v74
	v_add_f32_e32 v34, v45, v34
	v_pk_add_f32 v[22:23], v[22:23], v[26:27]
	v_lshlrev_b32_e32 v26, 16, v76
	v_and_b32_e32 v27, 0xffff0000, v76
	v_add_f32_e32 v34, v46, v34
	v_pk_mul_f32 v[48:49], v[40:41], v[40:41]
	v_pk_add_f32 v[26:27], v[18:19], v[26:27]
	v_lshlrev_b32_e32 v18, 16, v75
	v_and_b32_e32 v19, 0xffff0000, v75
	v_add_f32_e32 v34, v47, v34
	v_pk_add_f32 v[24:25], v[24:25], v[18:19]
	v_lshlrev_b32_e32 v18, 16, v77
	v_and_b32_e32 v19, 0xffff0000, v77
	v_add_f32_e32 v34, v48, v34
	v_pk_add_f32 v[28:29], v[20:21], v[18:19]
	v_pk_mul_f32 v[18:19], v[22:23], v[22:23]
	v_add_f32_e32 v34, v49, v34
	v_add_f32_e32 v18, v18, v34
	v_pk_mul_f32 v[20:21], v[24:25], v[24:25]
	v_add_f32_e32 v18, v19, v18
	v_add_f32_e32 v18, v20, v18
	v_pk_mul_f32 v[30:31], v[26:27], v[26:27]
	v_add_f32_e32 v18, v21, v18
	v_add_f32_e32 v18, v30, v18
	v_pk_mul_f32 v[32:33], v[28:29], v[28:29]
	v_add_f32_e32 v18, v31, v18
	s_mov_b64 s[12:13], 0x50100
	v_add_f32_e32 v18, v32, v18
	v_lshl_add_u64 v[36:37], v[156:157], 0, s[12:13]
	v_add_f32_e32 v30, v33, v18
	v_cvt_pk_bf16_f32 v18, v22, v23
	v_cvt_pk_bf16_f32 v19, v24, v25
	v_cvt_pk_bf16_f32 v20, v26, v27
	v_cvt_pk_bf16_f32 v21, v28, v29
	global_store_dwordx4 v[36:37], v[18:21], off
	s_nop 1
	v_xor_b32_e32 v18, 0x80000000, v30
	s_nop 1
	v_permlane16_swap_b32_e32 v30, v18
	s_nop 0
	v_add_f32_e32 v19, v30, v18
	v_and_b32_e32 v18, 0x7fffffff, v19
	v_or_b32_e32 v19, 0x80000000, v19
	s_nop 1
	v_permlane32_swap_b32_e32 v18, v19
	s_and_saveexec_b64 s[12:13], s[2:3]
	s_cbranch_execz .LBB0_1252
	v_add_f32_e32 v18, v18, v19
	v_and_b32_e32 v20, 0x7fffffff, v18
	v_add_u32_e32 v18, 0xa0, v154
	v_ashrrev_i32_e32 v19, 31, v18
	v_lshlrev_b64 v[18:19], 6, v[18:19]
	v_lshl_add_u64 v[18:19], s[10:11], 0, v[18:19]
	v_lshl_add_u64 v[18:19], s[8:9], 2, v[18:19]
	s_lshl_b32 s72, s16, 2
	v_lshl_add_u64 v[18:19], v[18:19], 0, s[72:73]
	global_store_dword v[18:19], v20, off
.LBB0_1252:
	s_or_b64 exec, exec, s[12:13]
	v_lshlrev_b32_e32 v22, 16, v70
	v_and_b32_e32 v23, 0xffff0000, v70
	v_pk_add_f32 v[14:15], v[14:15], v[22:23]
	v_lshlrev_b32_e32 v22, 16, v72
	v_and_b32_e32 v23, 0xffff0000, v72
	v_pk_add_f32 v[22:23], v[10:11], v[22:23]
	v_lshlrev_b32_e32 v10, 16, v71
	v_and_b32_e32 v11, 0xffff0000, v71
	v_pk_add_f32 v[16:17], v[16:17], v[10:11]
	v_lshlrev_b32_e32 v10, 16, v73
	v_and_b32_e32 v11, 0xffff0000, v73
	s_mov_b64 s[12:13], 0x58000
	v_pk_add_f32 v[24:25], v[12:13], v[10:11]
	v_lshl_add_u64 v[18:19], v[156:157], 0, s[12:13]
	v_pk_mul_f32 v[26:27], v[14:15], v[14:15]
	v_cvt_pk_bf16_f32 v10, v14, v15
	v_cvt_pk_bf16_f32 v11, v16, v17
	v_cvt_pk_bf16_f32 v12, v22, v23
	v_cvt_pk_bf16_f32 v13, v24, v25
	v_pk_mul_f32 v[28:29], v[16:17], v[16:17]
	global_store_dwordx4 v[18:19], v[10:13], off
	v_add_f32_e32 v18, v26, v27
	v_add_f32_e32 v18, v28, v18
	v_pk_mul_f32 v[30:31], v[22:23], v[22:23]
	v_lshlrev_b32_e32 v10, 16, v66
	v_and_b32_e32 v11, 0xffff0000, v66
	v_add_f32_e32 v18, v29, v18
	v_pk_add_f32 v[6:7], v[6:7], v[10:11]
	v_lshlrev_b32_e32 v10, 16, v68
	v_and_b32_e32 v11, 0xffff0000, v68
	v_add_f32_e32 v18, v30, v18
	v_pk_mul_f32 v[32:33], v[24:25], v[24:25]
	v_pk_add_f32 v[10:11], v[2:3], v[10:11]
	v_lshlrev_b32_e32 v2, 16, v67
	v_and_b32_e32 v3, 0xffff0000, v67
	v_add_f32_e32 v18, v31, v18
	v_pk_add_f32 v[8:9], v[8:9], v[2:3]
	v_lshlrev_b32_e32 v2, 16, v69
	v_and_b32_e32 v3, 0xffff0000, v69
	v_add_f32_e32 v18, v32, v18
	v_pk_add_f32 v[12:13], v[4:5], v[2:3]
	v_pk_mul_f32 v[2:3], v[6:7], v[6:7]
	v_add_f32_e32 v18, v33, v18
	v_add_f32_e32 v2, v2, v18
	v_pk_mul_f32 v[4:5], v[8:9], v[8:9]
	v_add_f32_e32 v2, v3, v2
	v_add_f32_e32 v2, v4, v2
	v_pk_mul_f32 v[14:15], v[10:11], v[10:11]
	v_add_f32_e32 v2, v5, v2
	v_add_f32_e32 v2, v14, v2
	v_pk_mul_f32 v[16:17], v[12:13], v[12:13]
	v_add_f32_e32 v2, v15, v2
	s_mov_b64 s[12:13], 0x58100
	v_add_f32_e32 v2, v16, v2
	v_lshl_add_u64 v[20:21], v[156:157], 0, s[12:13]
	v_add_f32_e32 v14, v17, v2
	v_cvt_pk_bf16_f32 v2, v6, v7
	v_cvt_pk_bf16_f32 v3, v8, v9
	v_cvt_pk_bf16_f32 v4, v10, v11
	v_cvt_pk_bf16_f32 v5, v12, v13
	global_store_dwordx4 v[20:21], v[2:5], off
	s_nop 1
	v_xor_b32_e32 v2, 0x80000000, v14
	s_nop 1
	v_permlane16_swap_b32_e32 v14, v2
	s_nop 0
	v_add_f32_e32 v3, v14, v2
	v_and_b32_e32 v2, 0x7fffffff, v3
	v_or_b32_e32 v3, 0x80000000, v3
	s_nop 1
	v_permlane32_swap_b32_e32 v2, v3
	s_and_saveexec_b64 s[12:13], s[2:3]
	s_cbranch_execz .LBB0_1254
	v_add_f32_e32 v2, v2, v3
	v_and_b32_e32 v4, 0x7fffffff, v2
	v_add_u32_e32 v2, 0xb0, v154
	v_ashrrev_i32_e32 v3, 31, v2
	v_lshlrev_b64 v[2:3], 6, v[2:3]
	v_lshl_add_u64 v[2:3], s[10:11], 0, v[2:3]
	v_lshl_add_u64 v[2:3], s[8:9], 2, v[2:3]
	s_lshl_b32 s72, s16, 2
	v_lshl_add_u64 v[2:3], v[2:3], 0, s[72:73]
	global_store_dword v[2:3], v4, off

; #define LAS __attribute__((address_space(3)))
; __device__ __forceinline__ void unpack8(const u32x4 w, float (&v)[8]) { v[0] = bflo(w.x); v[1] = bfhi(w.x); v[2] = bflo(w.y); v[3] = bfhi(w.y); v[4] = bflo(w.z); v[5] = bfhi(w.z); v[6] = bflo(w.w); v[7] = bfhi(w.w); }
; __device__ __forceinline__ u32x4 pack8(const float (&v)[8]) { u32x4 w; w.x = pk2(v[0], v[1]); w.y = pk2(v[2], v[3]); w.z = pk2(v[4], v[5]); w.w = pk2(v[6], v[7]); return w; }
;     __device__ __forceinline__ void row_group(Acc& acc, const int ai, const int m, const float (&xo0)[8], const float (&xo1)[8], bf16_t* xb0, const int row0, const int pn, const int wc, const int fq) const {
;         float ssq = 0.f;
; #pragma unroll
;         for (int bj = 0; bj < 2; ++bj) {
;             float v[8];
; #pragma unroll
;             for (int e = 0; e < 4; ++e) { const float a0 = bj ? xo1[e] : xo0[e], a1 = bj ? xo1[4 + e] : xo0[4 + e]; v[e] = dry ? a0 : a0 + acc[ai][bj][m][0][e]; v[4 + e] = dry ? a1 : a1 + acc[ai][bj][m][1][e]; }
; #pragma unroll
;             for (int e = 0; e < 8; ++e) ssq += v[e] * v[e];
;             gst<u32x4>(xb0 + (size_t)(ai * HALF + m * 16) * DM + bj * HALF, pack8(v));
;         }
;         ssq = xsum32p(xsum16p(ssq));
;         if (fq == 0) gst<float>(ss_next + (size_t)(row0 + ai * HALF + m * 16) * 16 + pn * 4 + wc, ssq);
;     }
;     __device__ __forceinline__ bool operator()(Acc& acc, const Unit& u, int wr, int wc, int fr, int fq, const LAS float*) const {
;         const int row0 = u.pm * BM + wr * 64 + fr, col0 = u.pn * BM + wc * 32 + 8 * fq;
;         bf16_t* xb0 = XB + (size_t)row0 * DM + col0; const float* xi0 = Xin + (size_t)row0 * DM + col0;
; #pragma unroll
;         for (int ai = 0; ai < 2; ++ai) {
;             u32x4 xv[4][2];
; #pragma unroll
;             for (int m = 0; m < 4; ++m)
; #pragma unroll
;                 for (int bj = 0; bj < 2; ++bj) xv[m][bj] = gld<u32x4>(xb0 + (size_t)(ai * HALF + m * 16) * DM + bj * HALF);
; #pragma unroll
;             for (int m = 0; m < 4; ++m) {
;                 float x0[8], x1[8]; unpack8(xv[m][0], x0); unpack8(xv[m][1], x1);
;                 row_group(acc, ai, m, x0, x1, xb0, row0, u.pn, wc, fq);
.LBB0_1575:
	v_mov_b32_e32 v130, v1
	s_lshl_b32 s2, s60, 8
	v_mbcnt_lo_u32_b32 v130, -1, v130
	v_mbcnt_hi_u32_b32 v130, -1, v130
	v_readlane_b32 s3, v250, 1
	v_bfe_u32 v163, v130, 4, 2
	s_add_i32 s2, s2, s3
	v_and_or_b32 v154, v130, 15, s2
	v_lshlrev_b32_e32 v130, 3, v163
	v_lshl_or_b32 v130, s59, 8, v130
	v_readlane_b32 s2, v250, 3
	v_ashrrev_i32_e32 v155, 31, v154
	v_lshlrev_b64 v[132:133], 11, v[154:155]
	v_or_b32_e32 v130, s2, v130
	v_readlane_b32 s2, v254, 49
	v_readlane_b32 s3, v254, 50
	v_ashrrev_i32_e32 v131, 31, v130
	s_lshl_b32 s8, s59, 2
	v_lshl_add_u64 v[132:133], s[2:3], 0, v[132:133]
	v_lshl_add_u64 v[156:157], v[130:131], 1, v[132:133]
	global_load_dwordx4 v[164:167], v[156:157], off
	global_load_dwordx4 v[168:171], v[156:157], off offset:256
	s_mov_b32 s2, 0x8000
	v_add_co_u32_e32 v130, vcc, s2, v156
	s_mov_b32 s2, 0x10000
	s_nop 0
	v_addc_co_u32_e32 v131, vcc, 0, v157, vcc
	v_add_co_u32_e32 v132, vcc, s2, v156
	s_mov_b32 s2, 0x18000
	s_nop 0
	v_addc_co_u32_e32 v133, vcc, 0, v157, vcc
	v_add_co_u32_e32 v172, vcc, s2, v156
	s_ashr_i32 s9, s8, 31
	s_nop 0
	v_addc_co_u32_e32 v173, vcc, 0, v157, vcc
	global_load_dwordx4 v[150:153], v[130:131], off
	global_load_dwordx4 v[146:149], v[130:131], off offset:256
	global_load_dwordx4 v[142:145], v[132:133], off
	global_load_dwordx4 v[138:141], v[132:133], off offset:256
	global_load_dwordx4 v[134:137], v[172:173], off
	s_nop 0
	global_load_dwordx4 v[130:133], v[172:173], off offset:256
	v_mov_b32_e32 v218, 0x40000
	v_mov_b32_e32 v219, 0
	v_lshl_add_u64 v[196:197], v[156:157], 0, v[218:219]
	global_load_dwordx4 v[180:183], v[196:197], off
	global_load_dwordx4 v[184:187], v[196:197], off offset:256
	v_mov_b32_e32 v218, 0x8000
	v_lshl_add_u64 v[196:197], v[196:197], 0, v[218:219]
	global_load_dwordx4 v[188:191], v[196:197], off
	global_load_dwordx4 v[192:195], v[196:197], off offset:256
	v_lshl_add_u64 v[196:197], v[196:197], 0, v[218:219]
	global_load_dwordx4 v[200:203], v[196:197], off
	global_load_dwordx4 v[206:209], v[196:197], off offset:256
	v_lshl_add_u64 v[196:197], v[196:197], 0, v[218:219]
	global_load_dwordx4 v[210:213], v[196:197], off
	global_load_dwordx4 v[214:217], v[196:197], off offset:256
	v_cmp_eq_u32_e64 s[2:3], 0, v163
	s_waitcnt vmcnt(15)
	v_lshlrev_b32_e32 v172, 16, v164
	v_and_b32_e32 v173, 0xffff0000, v164
	v_lshlrev_b32_e32 v174, 16, v166
	v_and_b32_e32 v175, 0xffff0000, v166
	v_lshlrev_b32_e32 v164, 16, v165
	v_and_b32_e32 v165, 0xffff0000, v165
	v_lshlrev_b32_e32 v166, 16, v167
	v_and_b32_e32 v167, 0xffff0000, v167
	s_waitcnt vmcnt(14)
	v_lshlrev_b32_e32 v176, 16, v168
	v_and_b32_e32 v177, 0xffff0000, v168
	v_lshlrev_b32_e32 v178, 16, v170
	v_and_b32_e32 v179, 0xffff0000, v170
	v_lshlrev_b32_e32 v168, 16, v169
	v_and_b32_e32 v169, 0xffff0000, v169
	v_lshlrev_b32_e32 v170, 16, v171
	v_and_b32_e32 v171, 0xffff0000, v171
	v_pk_add_f32 v[126:127], v[126:127], v[172:173]
	v_pk_add_f32 v[122:123], v[122:123], v[174:175]
	v_pk_add_f32 v[128:129], v[128:129], v[164:165]
	v_pk_add_f32 v[124:125], v[124:125], v[166:167]
	v_pk_add_f32 v[164:165], v[114:115], v[178:179]
	v_pk_add_f32 v[120:121], v[120:121], v[168:169]
	v_pk_add_f32 v[166:167], v[116:117], v[170:171]
	v_pk_mul_f32 v[168:169], v[126:127], v[126:127]
	v_cvt_pk_bf16_f32 v114, v126, v127
	v_cvt_pk_bf16_f32 v115, v128, v129
	v_cvt_pk_bf16_f32 v116, v122, v123
	v_cvt_pk_bf16_f32 v117, v124, v125
	v_pk_mul_f32 v[170:171], v[128:129], v[128:129]
	global_store_dwordx4 v[156:157], v[114:117], off
	v_pk_mul_f32 v[172:173], v[122:123], v[122:123]
	v_pk_mul_f32 v[174:175], v[124:125], v[124:125]
	v_add_f32_e32 v114, v168, v169
	v_add_f32_e32 v114, v170, v114
	v_add_f32_e32 v114, v171, v114
	v_add_f32_e32 v114, v172, v114
	v_add_f32_e32 v114, v173, v114
	v_pk_add_f32 v[118:119], v[118:119], v[176:177]
	v_add_f32_e32 v114, v174, v114
	v_pk_mul_f32 v[122:123], v[118:119], v[118:119]
	v_add_f32_e32 v114, v175, v114
	v_add_f32_e32 v114, v122, v114
	v_pk_mul_f32 v[124:125], v[120:121], v[120:121]
	v_add_f32_e32 v114, v123, v114
	v_add_f32_e32 v114, v124, v114
	v_pk_mul_f32 v[126:127], v[164:165], v[164:165]
	v_add_f32_e32 v114, v125, v114
	v_add_f32_e32 v114, v126, v114
	v_pk_mul_f32 v[128:129], v[166:167], v[166:167]
	v_add_f32_e32 v114, v127, v114
	v_add_f32_e32 v114, v128, v114
	v_add_f32_e32 v114, v129, v114
	v_xor_b32_e32 v115, 0x80000000, v114
	s_nop 1
	v_permlane16_swap_b32_e32 v114, v115
	v_cvt_pk_bf16_f32 v118, v118, v119
	v_add_f32_e32 v115, v114, v115
	v_and_b32_e32 v114, 0x7fffffff, v115
	v_or_b32_e32 v115, 0x80000000, v115
	v_cvt_pk_bf16_f32 v119, v120, v121
	v_cvt_pk_bf16_f32 v120, v164, v165
	v_cvt_pk_bf16_f32 v121, v166, v167
	v_permlane32_swap_b32_e32 v114, v115
	global_store_dwordx4 v[156:157], v[118:121], off offset:256
	s_and_saveexec_b64 s[12:13], s[2:3]
	v_readlane_b32 s16, v254, 35
	s_cbranch_execz .LBB0_1577
	v_readlane_b32 s14, v254, 51
	v_lshlrev_b64 v[116:117], 6, v[154:155]
	v_readlane_b32 s15, v254, 52
	s_lshl_b32 s72, s16, 2
	v_add_f32_e32 v114, v114, v115
	v_lshl_add_u64 v[116:117], s[14:15], 0, v[116:117]
	v_lshl_add_u64 v[116:117], s[8:9], 2, v[116:117]
	v_lshl_add_u64 v[116:117], v[116:117], 0, s[72:73]
	v_and_b32_e32 v114, 0x7fffffff, v114
	global_store_dword v[116:117], v114, off
; __device__ __forceinline__ void unpack8(const u32x4 w, float (&v)[8]) { v[0] = bflo(w.x); v[1] = bfhi(w.x); v[2] = bflo(w.y); v[3] = bfhi(w.y); v[4] = bflo(w.z); v[5] = bfhi(w.z); v[6] = bflo(w.w); v[7] = bfhi(w.w); }
; __device__ __forceinline__ u32x4 pack8(const float (&v)[8]) { u32x4 w; w.x = pk2(v[0], v[1]); w.y = pk2(v[2], v[3]); w.z = pk2(v[4], v[5]); w.w = pk2(v[6], v[7]); return w; }
; __device__ __forceinline__ float xsum16p(float x) { const unsigned u = __builtin_bit_cast(unsigned, x); const auto r = __builtin_amdgcn_permlane16_swap(u, u ^ 0x80000000u, false, false); unsigned r0 = r[0], r1 = r[1]; asm("" : "+v"(r0), "+v"(r1)); return fabsf(__builtin_bit_cast(float, r0) + __builtin_bit_cast(float, r1)); }
;     __device__ __forceinline__ void row_group(Acc& acc, const int ai, const int m, const float (&xo0)[8], const float (&xo1)[8], bf16_t* xb0, const int row0, const int pn, const int wc, const int fq) const {
;         float ssq = 0.f;
; #pragma unroll
;         for (int bj = 0; bj < 2; ++bj) {
;             float v[8];
; #pragma unroll
;             for (int e = 0; e < 4; ++e) { const float a0 = bj ? xo1[e] : xo0[e], a1 = bj ? xo1[4 + e] : xo0[4 + e]; v[e] = dry ? a0 : a0 + acc[ai][bj][m][0][e]; v[4 + e] = dry ? a1 : a1 + acc[ai][bj][m][1][e]; }
; #pragma unroll
;             for (int e = 0; e < 8; ++e) ssq += v[e] * v[e];
;             gst<u32x4>(xb0 + (size_t)(ai * HALF + m * 16) * DM + bj * HALF, pack8(v));
;         }
;         ssq = xsum32p(xsum16p(ssq));
;         if (fq == 0) gst<float>(ss_next + (size_t)(row0 + ai * HALF + m * 16) * 16 + pn * 4 + wc, ssq);
;     }
;     __device__ __forceinline__ bool operator()(Acc& acc, const Unit& u, int wr, int wc, int fr, int fq, const LAS float*) const {
;     ...
;             for (int m = 0; m < 4; ++m)
; #pragma unroll
;                 for (int bj = 0; bj < 2; ++bj) xv[m][bj] = gld<u32x4>(xb0 + (size_t)(ai * HALF + m * 16) * DM + bj * HALF);
; #pragma unroll
;             for (int m = 0; m < 4; ++m) {
;                 float x0[8], x1[8]; unpack8(xv[m][0], x0); unpack8(xv[m][1], x1);
;                 row_group(acc, ai, m, x0, x1, xb0, row0, u.pn, wc, fq);
;             }
.LBB0_1577:
	s_or_b64 exec, exec, s[12:13]
	s_waitcnt vmcnt(15)
	v_lshlrev_b32_e32 v118, 16, v150
	v_and_b32_e32 v119, 0xffff0000, v150
	v_pk_add_f32 v[110:111], v[110:111], v[118:119]
	v_lshlrev_b32_e32 v118, 16, v152
	v_and_b32_e32 v119, 0xffff0000, v152
	v_pk_add_f32 v[118:119], v[106:107], v[118:119]
	v_lshlrev_b32_e32 v106, 16, v151
	v_and_b32_e32 v107, 0xffff0000, v151
	v_pk_add_f32 v[112:113], v[112:113], v[106:107]
	v_lshlrev_b32_e32 v106, 16, v153
	v_and_b32_e32 v107, 0xffff0000, v153
	s_mov_b64 s[12:13], 0x8000
	v_pk_add_f32 v[120:121], v[108:109], v[106:107]
	v_lshl_add_u64 v[114:115], v[156:157], 0, s[12:13]
	v_pk_mul_f32 v[122:123], v[110:111], v[110:111]
	v_cvt_pk_bf16_f32 v106, v110, v111
	v_cvt_pk_bf16_f32 v107, v112, v113
	v_cvt_pk_bf16_f32 v108, v118, v119
	v_cvt_pk_bf16_f32 v109, v120, v121
	v_pk_mul_f32 v[124:125], v[112:113], v[112:113]
	global_store_dwordx4 v[114:115], v[106:109], off
	v_add_f32_e32 v114, v122, v123
	v_add_f32_e32 v114, v124, v114
	v_pk_mul_f32 v[126:127], v[118:119], v[118:119]
	s_waitcnt vmcnt(15)
	v_lshlrev_b32_e32 v106, 16, v146
	v_and_b32_e32 v107, 0xffff0000, v146
	v_add_f32_e32 v114, v125, v114
	v_pk_add_f32 v[102:103], v[102:103], v[106:107]
	v_lshlrev_b32_e32 v106, 16, v148
	v_and_b32_e32 v107, 0xffff0000, v148
	v_add_f32_e32 v114, v126, v114
	v_pk_mul_f32 v[128:129], v[120:121], v[120:121]
	v_pk_add_f32 v[106:107], v[98:99], v[106:107]
	v_lshlrev_b32_e32 v98, 16, v147
	v_and_b32_e32 v99, 0xffff0000, v147
	v_add_f32_e32 v114, v127, v114
	v_pk_add_f32 v[104:105], v[104:105], v[98:99]
	v_lshlrev_b32_e32 v98, 16, v149
	v_and_b32_e32 v99, 0xffff0000, v149
	v_add_f32_e32 v114, v128, v114
	v_pk_add_f32 v[108:109], v[100:101], v[98:99]
	v_pk_mul_f32 v[98:99], v[102:103], v[102:103]
	v_add_f32_e32 v114, v129, v114
	v_add_f32_e32 v98, v98, v114
	v_pk_mul_f32 v[100:101], v[104:105], v[104:105]
	v_add_f32_e32 v98, v99, v98
	v_add_f32_e32 v98, v100, v98
	v_pk_mul_f32 v[110:111], v[106:107], v[106:107]
	v_add_f32_e32 v98, v101, v98
	v_add_f32_e32 v98, v110, v98
	v_pk_mul_f32 v[112:113], v[108:109], v[108:109]
	v_add_f32_e32 v98, v111, v98
	s_mov_b64 s[12:13], 0x8100
	v_add_f32_e32 v98, v112, v98
	v_lshl_add_u64 v[116:117], v[156:157], 0, s[12:13]
	v_add_f32_e32 v110, v113, v98
	v_cvt_pk_bf16_f32 v98, v102, v103
	v_cvt_pk_bf16_f32 v99, v104, v105
	v_cvt_pk_bf16_f32 v100, v106, v107
	v_cvt_pk_bf16_f32 v101, v108, v109
	global_store_dwordx4 v[116:117], v[98:101], off
	s_nop 1
	v_xor_b32_e32 v98, 0x80000000, v110
	s_nop 1
	v_permlane16_swap_b32_e32 v110, v98
	s_nop 0
	v_add_f32_e32 v99, v110, v98
	v_and_b32_e32 v98, 0x7fffffff, v99
	v_or_b32_e32 v99, 0x80000000, v99
	s_nop 1
	v_permlane32_swap_b32_e32 v98, v99
	s_and_saveexec_b64 s[12:13], s[2:3]
	s_cbranch_execz .LBB0_1579
	v_add_f32_e32 v98, v98, v99
	v_and_b32_e32 v100, 0x7fffffff, v98
	v_or_b32_e32 v98, 16, v154
	v_ashrrev_i32_e32 v99, 31, v98
	v_readlane_b32 s14, v254, 51
	v_lshlrev_b64 v[98:99], 6, v[98:99]
	v_readlane_b32 s15, v254, 52
	s_lshl_b32 s72, s16, 2
	s_nop 0
	v_lshl_add_u64 v[98:99], s[14:15], 0, v[98:99]
	v_lshl_add_u64 v[98:99], s[8:9], 2, v[98:99]
	v_lshl_add_u64 v[98:99], v[98:99], 0, s[72:73]
	global_store_dword v[98:99], v100, off
.LBB0_1579:
	s_or_b64 exec, exec, s[12:13]
	s_waitcnt vmcnt(15)
	v_lshlrev_b32_e32 v102, 16, v142
	v_and_b32_e32 v103, 0xffff0000, v142
	v_pk_add_f32 v[94:95], v[94:95], v[102:103]
	v_lshlrev_b32_e32 v102, 16, v144
	v_and_b32_e32 v103, 0xffff0000, v144
	v_pk_add_f32 v[102:103], v[90:91], v[102:103]
	v_lshlrev_b32_e32 v90, 16, v143
	v_and_b32_e32 v91, 0xffff0000, v143
	v_pk_add_f32 v[96:97], v[96:97], v[90:91]
	v_lshlrev_b32_e32 v90, 16, v145
	v_and_b32_e32 v91, 0xffff0000, v145
	s_mov_b64 s[12:13], 0x10000
	v_pk_add_f32 v[104:105], v[92:93], v[90:91]
	v_lshl_add_u64 v[98:99], v[156:157], 0, s[12:13]
	v_pk_mul_f32 v[106:107], v[94:95], v[94:95]
	v_cvt_pk_bf16_f32 v90, v94, v95
	v_cvt_pk_bf16_f32 v91, v96, v97
	v_cvt_pk_bf16_f32 v92, v102, v103
	v_cvt_pk_bf16_f32 v93, v104, v105
	v_pk_mul_f32 v[108:109], v[96:97], v[96:97]
	global_store_dwordx4 v[98:99], v[90:93], off
	v_add_f32_e32 v98, v106, v107
	v_add_f32_e32 v98, v108, v98
	v_pk_mul_f32 v[110:111], v[102:103], v[102:103]
	s_waitcnt vmcnt(15)
	v_lshlrev_b32_e32 v90, 16, v138
	v_and_b32_e32 v91, 0xffff0000, v138
	v_add_f32_e32 v98, v109, v98
	v_pk_add_f32 v[86:87], v[86:87], v[90:91]
	v_lshlrev_b32_e32 v90, 16, v140
	v_and_b32_e32 v91, 0xffff0000, v140
	v_add_f32_e32 v98, v110, v98
	v_pk_mul_f32 v[112:113], v[104:105], v[104:105]
	v_pk_add_f32 v[90:91], v[82:83], v[90:91]
	v_lshlrev_b32_e32 v82, 16, v139
	v_and_b32_e32 v83, 0xffff0000, v139
	v_add_f32_e32 v98, v111, v98
	v_pk_add_f32 v[88:89], v[88:89], v[82:83]
	v_lshlrev_b32_e32 v82, 16, v141
	v_and_b32_e32 v83, 0xffff0000, v141
	v_add_f32_e32 v98, v112, v98
	v_pk_add_f32 v[92:93], v[84:85], v[82:83]
	v_pk_mul_f32 v[82:83], v[86:87], v[86:87]
	v_add_f32_e32 v98, v113, v98
	v_add_f32_e32 v82, v82, v98
	v_pk_mul_f32 v[84:85], v[88:89], v[88:89]
	v_add_f32_e32 v82, v83, v82
	v_add_f32_e32 v82, v84, v82
	v_pk_mul_f32 v[94:95], v[90:91], v[90:91]
	v_add_f32_e32 v82, v85, v82
	v_add_f32_e32 v82, v94, v82
	v_pk_mul_f32 v[96:97], v[92:93], v[92:93]
	v_add_f32_e32 v82, v95, v82
	s_mov_b64 s[12:13], 0x10100
	v_add_f32_e32 v82, v96, v82
	v_lshl_add_u64 v[100:101], v[156:157], 0, s[12:13]
	v_add_f32_e32 v94, v97, v82
	v_cvt_pk_bf16_f32 v82, v86, v87
	v_cvt_pk_bf16_f32 v83, v88, v89
	v_cvt_pk_bf16_f32 v84, v90, v91
	v_cvt_pk_bf16_f32 v85, v92, v93
	global_store_dwordx4 v[100:101], v[82:85], off
	s_nop 1
	v_xor_b32_e32 v82, 0x80000000, v94
	s_nop 1
	v_permlane16_swap_b32_e32 v94, v82
	s_nop 0
	v_add_f32_e32 v83, v94, v82
	v_and_b32_e32 v82, 0x7fffffff, v83
	v_or_b32_e32 v83, 0x80000000, v83
	s_nop 1
	v_permlane32_swap_b32_e32 v82, v83
	s_and_saveexec_b64 s[12:13], s[2:3]
	s_cbranch_execz .LBB0_1581
	v_add_f32_e32 v82, v82, v83
	v_and_b32_e32 v84, 0x7fffffff, v82
	v_or_b32_e32 v82, 32, v154
	v_ashrrev_i32_e32 v83, 31, v82
	v_readlane_b32 s14, v254, 51
	v_lshlrev_b64 v[82:83], 6, v[82:83]
	v_readlane_b32 s15, v254, 52
	s_lshl_b32 s72, s16, 2
	s_nop 0
	v_lshl_add_u64 v[82:83], s[14:15], 0, v[82:83]
	v_lshl_add_u64 v[82:83], s[8:9], 2, v[82:83]
	v_lshl_add_u64 v[82:83], v[82:83], 0, s[72:73]
	global_store_dword v[82:83], v84, off
; __device__ __forceinline__ void unpack8(const u32x4 w, float (&v)[8]) { v[0] = bflo(w.x); v[1] = bfhi(w.x); v[2] = bflo(w.y); v[3] = bfhi(w.y); v[4] = bflo(w.z); v[5] = bfhi(w.z); v[6] = bflo(w.w); v[7] = bfhi(w.w); }
; __device__ __forceinline__ u32x4 pack8(const float (&v)[8]) { u32x4 w; w.x = pk2(v[0], v[1]); w.y = pk2(v[2], v[3]); w.z = pk2(v[4], v[5]); w.w = pk2(v[6], v[7]); return w; }
; __device__ __forceinline__ float xsum16p(float x) { const unsigned u = __builtin_bit_cast(unsigned, x); const auto r = __builtin_amdgcn_permlane16_swap(u, u ^ 0x80000000u, false, false); unsigned r0 = r[0], r1 = r[1]; asm("" : "+v"(r0), "+v"(r1)); return fabsf(__builtin_bit_cast(float, r0) + __builtin_bit_cast(float, r1)); }
;     __device__ __forceinline__ void row_group(Acc& acc, const int ai, const int m, const float (&xo0)[8], const float (&xo1)[8], bf16_t* xb0, const int row0, const int pn, const int wc, const int fq) const {
;         float ssq = 0.f;
; #pragma unroll
;         for (int bj = 0; bj < 2; ++bj) {
;             float v[8];
; #pragma unroll
;             for (int e = 0; e < 4; ++e) { const float a0 = bj ? xo1[e] : xo0[e], a1 = bj ? xo1[4 + e] : xo0[4 + e]; v[e] = dry ? a0 : a0 + acc[ai][bj][m][0][e]; v[4 + e] = dry ? a1 : a1 + acc[ai][bj][m][1][e]; }
; #pragma unroll
;             for (int e = 0; e < 8; ++e) ssq += v[e] * v[e];
;             gst<u32x4>(xb0 + (size_t)(ai * HALF + m * 16) * DM + bj * HALF, pack8(v));
;         }
;         ssq = xsum32p(xsum16p(ssq));
;         if (fq == 0) gst<float>(ss_next + (size_t)(row0 + ai * HALF + m * 16) * 16 + pn * 4 + wc, ssq);
;     }
;     __device__ __forceinline__ bool operator()(Acc& acc, const Unit& u, int wr, int wc, int fr, int fq, const LAS float*) const {
;     ...
;             for (int m = 0; m < 4; ++m)
; #pragma unroll
;                 for (int bj = 0; bj < 2; ++bj) xv[m][bj] = gld<u32x4>(xb0 + (size_t)(ai * HALF + m * 16) * DM + bj * HALF);
; #pragma unroll
;             for (int m = 0; m < 4; ++m) {
;                 float x0[8], x1[8]; unpack8(xv[m][0], x0); unpack8(xv[m][1], x1);
;                 row_group(acc, ai, m, x0, x1, xb0, row0, u.pn, wc, fq);
;             }
.LBB0_1581:
	s_or_b64 exec, exec, s[12:13]
	s_waitcnt vmcnt(15)
	v_lshlrev_b32_e32 v86, 16, v134
	v_and_b32_e32 v87, 0xffff0000, v134
	v_pk_add_f32 v[78:79], v[78:79], v[86:87]
	v_lshlrev_b32_e32 v86, 16, v136
	v_and_b32_e32 v87, 0xffff0000, v136
	v_pk_add_f32 v[86:87], v[74:75], v[86:87]
	v_lshlrev_b32_e32 v74, 16, v135
	v_and_b32_e32 v75, 0xffff0000, v135
	v_pk_add_f32 v[80:81], v[80:81], v[74:75]
	v_lshlrev_b32_e32 v74, 16, v137
	v_and_b32_e32 v75, 0xffff0000, v137
	s_mov_b64 s[12:13], 0x18000
	v_pk_add_f32 v[88:89], v[76:77], v[74:75]
	v_lshl_add_u64 v[82:83], v[156:157], 0, s[12:13]
	v_pk_mul_f32 v[90:91], v[78:79], v[78:79]
	v_cvt_pk_bf16_f32 v74, v78, v79
	v_cvt_pk_bf16_f32 v75, v80, v81
	v_cvt_pk_bf16_f32 v76, v86, v87
	v_cvt_pk_bf16_f32 v77, v88, v89
	v_pk_mul_f32 v[92:93], v[80:81], v[80:81]
	global_store_dwordx4 v[82:83], v[74:77], off
	v_add_f32_e32 v82, v90, v91
	v_add_f32_e32 v82, v92, v82
	v_pk_mul_f32 v[94:95], v[86:87], v[86:87]
	s_waitcnt vmcnt(15)
	v_lshlrev_b32_e32 v74, 16, v130
	v_and_b32_e32 v75, 0xffff0000, v130
	v_add_f32_e32 v82, v93, v82
	v_pk_add_f32 v[70:71], v[70:71], v[74:75]
	v_lshlrev_b32_e32 v74, 16, v132
	v_and_b32_e32 v75, 0xffff0000, v132
	v_add_f32_e32 v82, v94, v82
	v_pk_mul_f32 v[96:97], v[88:89], v[88:89]
	v_pk_add_f32 v[74:75], v[66:67], v[74:75]
	v_lshlrev_b32_e32 v66, 16, v131
	v_and_b32_e32 v67, 0xffff0000, v131
	v_add_f32_e32 v82, v95, v82
	v_pk_add_f32 v[72:73], v[72:73], v[66:67]
	v_lshlrev_b32_e32 v66, 16, v133
	v_and_b32_e32 v67, 0xffff0000, v133
	v_add_f32_e32 v82, v96, v82
	v_pk_add_f32 v[76:77], v[68:69], v[66:67]
	v_pk_mul_f32 v[66:67], v[70:71], v[70:71]
	v_add_f32_e32 v82, v97, v82
	v_add_f32_e32 v66, v66, v82
	v_pk_mul_f32 v[68:69], v[72:73], v[72:73]
	v_add_f32_e32 v66, v67, v66
	v_add_f32_e32 v66, v68, v66
	v_pk_mul_f32 v[78:79], v[74:75], v[74:75]
	v_add_f32_e32 v66, v69, v66
	v_add_f32_e32 v66, v78, v66
	v_pk_mul_f32 v[80:81], v[76:77], v[76:77]
	v_add_f32_e32 v66, v79, v66
	s_mov_b64 s[12:13], 0x18100
	v_add_f32_e32 v66, v80, v66
	v_lshl_add_u64 v[84:85], v[156:157], 0, s[12:13]
	v_add_f32_e32 v78, v81, v66
	v_cvt_pk_bf16_f32 v66, v70, v71
	v_cvt_pk_bf16_f32 v67, v72, v73
	v_cvt_pk_bf16_f32 v68, v74, v75
	v_cvt_pk_bf16_f32 v69, v76, v77
	global_store_dwordx4 v[84:85], v[66:69], off
	s_nop 1
	v_xor_b32_e32 v66, 0x80000000, v78
	s_nop 1
	v_permlane16_swap_b32_e32 v78, v66
	s_nop 0
	v_add_f32_e32 v67, v78, v66
	v_and_b32_e32 v66, 0x7fffffff, v67
	v_or_b32_e32 v67, 0x80000000, v67
	s_nop 1
	v_permlane32_swap_b32_e32 v66, v67
	s_and_saveexec_b64 s[12:13], s[2:3]
	s_cbranch_execz .LBB0_1583
	v_add_f32_e32 v66, v66, v67
	v_and_b32_e32 v68, 0x7fffffff, v66
	v_or_b32_e32 v66, 48, v154
	v_ashrrev_i32_e32 v67, 31, v66
	v_readlane_b32 s14, v254, 51
	v_lshlrev_b64 v[66:67], 6, v[66:67]
	v_readlane_b32 s15, v254, 52
	s_lshl_b32 s72, s16, 2
	s_nop 0
	v_lshl_add_u64 v[66:67], s[14:15], 0, v[66:67]
	v_lshl_add_u64 v[66:67], s[8:9], 2, v[66:67]
	v_lshl_add_u64 v[66:67], v[66:67], 0, s[72:73]
	global_store_dword v[66:67], v68, off
.LBB0_1583:
	s_or_b64 exec, exec, s[12:13]
	s_waitcnt vmcnt(8)
	v_add_co_u32_e32 v90, vcc, 0x40000, v156
	s_nop 1
	v_addc_co_u32_e32 v91, vcc, 0, v157, vcc
	v_mov_b64_e32 v[92:93], v[180:181]
	v_mov_b64_e32 v[94:95], v[182:183]
	v_mov_b64_e32 v[96:97], v[184:185]
	v_mov_b64_e32 v[98:99], v[186:187]
	v_add_co_u32_e32 v66, vcc, 0x48000, v156
	v_lshlrev_b32_e32 v100, 16, v92
	v_addc_co_u32_e32 v67, vcc, 0, v157, vcc
	v_mov_b64_e32 v[86:87], v[188:189]
	v_mov_b64_e32 v[88:89], v[190:191]
	v_mov_b64_e32 v[82:83], v[192:193]
	v_mov_b64_e32 v[84:85], v[194:195]
	v_add_co_u32_e32 v66, vcc, 0x50000, v156
	v_and_b32_e32 v101, 0xffff0000, v92
	s_nop 0
	v_addc_co_u32_e32 v67, vcc, 0, v157, vcc
	v_mov_b64_e32 v[78:79], v[200:201]
	v_mov_b64_e32 v[80:81], v[202:203]
	v_mov_b64_e32 v[74:75], v[206:207]
	v_mov_b64_e32 v[76:77], v[208:209]
	v_add_co_u32_e32 v66, vcc, 0x58000, v156
	v_pk_add_f32 v[62:63], v[62:63], v[100:101]
	s_nop 0
	v_addc_co_u32_e32 v67, vcc, 0, v157, vcc
	v_mov_b64_e32 v[70:71], v[210:211]
	v_mov_b64_e32 v[72:73], v[212:213]
	s_nop 0
	v_mov_b64_e32 v[66:67], v[214:215]
	v_mov_b64_e32 v[68:69], v[216:217]
	v_lshlrev_b32_e32 v100, 16, v94
	v_and_b32_e32 v101, 0xffff0000, v94
	v_pk_add_f32 v[100:101], v[58:59], v[100:101]
	v_lshlrev_b32_e32 v58, 16, v93
	v_and_b32_e32 v59, 0xffff0000, v93
	v_pk_add_f32 v[64:65], v[64:65], v[58:59]
	v_lshlrev_b32_e32 v58, 16, v95
	v_and_b32_e32 v59, 0xffff0000, v95
	v_pk_add_f32 v[92:93], v[60:61], v[58:59]
	v_pk_mul_f32 v[94:95], v[62:63], v[62:63]
	v_pk_mul_f32 v[102:103], v[64:65], v[64:65]
	v_pk_mul_f32 v[106:107], v[92:93], v[92:93]
	v_cvt_pk_bf16_f32 v61, v92, v93
	v_add_f32_e32 v92, v94, v95
	v_cvt_pk_bf16_f32 v58, v62, v63
	v_cvt_pk_bf16_f32 v59, v64, v65
	v_cvt_pk_bf16_f32 v60, v100, v101
	v_add_f32_e32 v92, v102, v92
	v_pk_mul_f32 v[104:105], v[100:101], v[100:101]
	global_store_dwordx4 v[90:91], v[58:61], off
	v_add_f32_e32 v92, v103, v92
	v_add_f32_e32 v92, v104, v92
	v_lshlrev_b32_e32 v58, 16, v96
	v_and_b32_e32 v59, 0xffff0000, v96
	v_pk_add_f32 v[54:55], v[54:55], v[58:59]
	v_lshlrev_b32_e32 v58, 16, v98
	v_and_b32_e32 v59, 0xffff0000, v98
	v_pk_add_f32 v[58:59], v[50:51], v[58:59]
	v_lshlrev_b32_e32 v50, 16, v97
	v_and_b32_e32 v51, 0xffff0000, v97
	v_add_f32_e32 v92, v105, v92
	v_pk_add_f32 v[56:57], v[56:57], v[50:51]
	v_lshlrev_b32_e32 v50, 16, v99
	v_and_b32_e32 v51, 0xffff0000, v99
	v_add_f32_e32 v92, v106, v92
	v_pk_add_f32 v[60:61], v[52:53], v[50:51]
	v_pk_mul_f32 v[50:51], v[54:55], v[54:55]
	v_add_f32_e32 v92, v107, v92
	v_add_f32_e32 v50, v50, v92
	v_pk_mul_f32 v[52:53], v[56:57], v[56:57]
	v_add_f32_e32 v50, v51, v50
	v_add_f32_e32 v50, v52, v50
	v_pk_mul_f32 v[62:63], v[58:59], v[58:59]
	v_add_f32_e32 v50, v53, v50
	v_add_f32_e32 v50, v62, v50
	v_pk_mul_f32 v[64:65], v[60:61], v[60:61]
	v_add_f32_e32 v50, v63, v50
	v_add_f32_e32 v50, v64, v50
	v_add_f32_e32 v62, v65, v50
	v_cvt_pk_bf16_f32 v50, v54, v55
	v_cvt_pk_bf16_f32 v51, v56, v57
	v_cvt_pk_bf16_f32 v52, v58, v59
	v_cvt_pk_bf16_f32 v53, v60, v61
	global_store_dwordx4 v[90:91], v[50:53], off offset:256
	s_nop 1
	v_xor_b32_e32 v50, 0x80000000, v62
	s_nop 1
	v_permlane16_swap_b32_e32 v62, v50
	s_nop 0
	v_add_f32_e32 v51, v62, v50
	v_and_b32_e32 v50, 0x7fffffff, v51
	v_or_b32_e32 v51, 0x80000000, v51
	s_nop 1
	v_permlane32_swap_b32_e32 v50, v51
	s_and_saveexec_b64 s[12:13], s[2:3]
	s_cbranch_execz .LBB0_1585
	v_add_f32_e32 v50, v50, v51
	v_and_b32_e32 v52, 0x7fffffff, v50
	v_add_u32_e32 v50, 0x80, v154
	v_ashrrev_i32_e32 v51, 31, v50
	v_readlane_b32 s14, v254, 51
	v_lshlrev_b64 v[50:51], 6, v[50:51]
	v_readlane_b32 s15, v254, 52
	s_lshl_b32 s72, s16, 2
	s_nop 0
	v_lshl_add_u64 v[50:51], s[14:15], 0, v[50:51]
	v_lshl_add_u64 v[50:51], s[8:9], 2, v[50:51]
	v_lshl_add_u64 v[50:51], v[50:51], 0, s[72:73]
	global_store_dword v[50:51], v52, off
; __device__ __forceinline__ u32x4 pack8(const float (&v)[8]) { u32x4 w; w.x = pk2(v[0], v[1]); w.y = pk2(v[2], v[3]); w.z = pk2(v[4], v[5]); w.w = pk2(v[6], v[7]); return w; }
; __device__ __forceinline__ float xsum16p(float x) { const unsigned u = __builtin_bit_cast(unsigned, x); const auto r = __builtin_amdgcn_permlane16_swap(u, u ^ 0x80000000u, false, false); unsigned r0 = r[0], r1 = r[1]; asm("" : "+v"(r0), "+v"(r1)); return fabsf(__builtin_bit_cast(float, r0) + __builtin_bit_cast(float, r1)); }
; __device__ __forceinline__ float xsum32p(float x) { const unsigned u = __builtin_bit_cast(unsigned, x); const auto r = __builtin_amdgcn_permlane32_swap(u, u ^ 0x80000000u, false, false); unsigned r0 = r[0], r1 = r[1]; asm("" : "+v"(r0), "+v"(r1)); return fabsf(__builtin_bit_cast(float, r0) + __builtin_bit_cast(float, r1)); }
;     __device__ __forceinline__ void row_group(Acc& acc, const int ai, const int m, const float (&xo0)[8], const float (&xo1)[8], bf16_t* xb0, const int row0, const int pn, const int wc, const int fq) const {
;         float ssq = 0.f;
; #pragma unroll
;         for (int bj = 0; bj < 2; ++bj) {
;             float v[8];
; #pragma unroll
;             for (int e = 0; e < 4; ++e) { const float a0 = bj ? xo1[e] : xo0[e], a1 = bj ? xo1[4 + e] : xo0[4 + e]; v[e] = dry ? a0 : a0 + acc[ai][bj][m][0][e]; v[4 + e] = dry ? a1 : a1 + acc[ai][bj][m][1][e]; }
; #pragma unroll
;             for (int e = 0; e < 8; ++e) ssq += v[e] * v[e];
;             gst<u32x4>(xb0 + (size_t)(ai * HALF + m * 16) * DM + bj * HALF, pack8(v));
;         }
;         ssq = xsum32p(xsum16p(ssq));
;         if (fq == 0) gst<float>(ss_next + (size_t)(row0 + ai * HALF + m * 16) * 16 + pn * 4 + wc, ssq);
;     }
.LBB0_1585:
	s_or_b64 exec, exec, s[12:13]
	v_lshlrev_b32_e32 v54, 16, v86
	v_and_b32_e32 v55, 0xffff0000, v86
	v_pk_add_f32 v[46:47], v[46:47], v[54:55]
	v_lshlrev_b32_e32 v54, 16, v88
	v_and_b32_e32 v55, 0xffff0000, v88
	v_pk_add_f32 v[54:55], v[42:43], v[54:55]
	v_lshlrev_b32_e32 v42, 16, v87
	v_and_b32_e32 v43, 0xffff0000, v87
	v_pk_add_f32 v[48:49], v[48:49], v[42:43]
	v_lshlrev_b32_e32 v42, 16, v89
	v_and_b32_e32 v43, 0xffff0000, v89
	s_mov_b64 s[12:13], 0x48000
	v_pk_add_f32 v[56:57], v[44:45], v[42:43]
	v_lshl_add_u64 v[50:51], v[156:157], 0, s[12:13]
	v_pk_mul_f32 v[58:59], v[46:47], v[46:47]
	v_cvt_pk_bf16_f32 v42, v46, v47
	v_cvt_pk_bf16_f32 v43, v48, v49
	v_cvt_pk_bf16_f32 v44, v54, v55
	v_cvt_pk_bf16_f32 v45, v56, v57
	v_pk_mul_f32 v[60:61], v[48:49], v[48:49]
	global_store_dwordx4 v[50:51], v[42:45], off
	v_add_f32_e32 v50, v58, v59
	v_add_f32_e32 v50, v60, v50
	v_pk_mul_f32 v[62:63], v[54:55], v[54:55]
	v_lshlrev_b32_e32 v42, 16, v82
	v_and_b32_e32 v43, 0xffff0000, v82
	v_add_f32_e32 v50, v61, v50
	v_pk_add_f32 v[38:39], v[38:39], v[42:43]
	v_lshlrev_b32_e32 v42, 16, v84
	v_and_b32_e32 v43, 0xffff0000, v84
	v_add_f32_e32 v50, v62, v50
	v_pk_mul_f32 v[64:65], v[56:57], v[56:57]
	v_pk_add_f32 v[42:43], v[34:35], v[42:43]
	v_lshlrev_b32_e32 v34, 16, v83
	v_and_b32_e32 v35, 0xffff0000, v83
	v_add_f32_e32 v50, v63, v50
	v_pk_add_f32 v[40:41], v[40:41], v[34:35]
	v_lshlrev_b32_e32 v34, 16, v85
	v_and_b32_e32 v35, 0xffff0000, v85
	v_add_f32_e32 v50, v64, v50
	v_pk_add_f32 v[44:45], v[36:37], v[34:35]
	v_pk_mul_f32 v[34:35], v[38:39], v[38:39]
	v_add_f32_e32 v50, v65, v50
	v_add_f32_e32 v34, v34, v50
	v_pk_mul_f32 v[36:37], v[40:41], v[40:41]
	v_add_f32_e32 v34, v35, v34
	v_add_f32_e32 v34, v36, v34
	v_pk_mul_f32 v[46:47], v[42:43], v[42:43]
	v_add_f32_e32 v34, v37, v34
	v_add_f32_e32 v34, v46, v34
	v_pk_mul_f32 v[48:49], v[44:45], v[44:45]
	v_add_f32_e32 v34, v47, v34
	s_mov_b64 s[12:13], 0x48100
	v_add_f32_e32 v34, v48, v34
	v_lshl_add_u64 v[52:53], v[156:157], 0, s[12:13]
	v_add_f32_e32 v46, v49, v34
	v_cvt_pk_bf16_f32 v34, v38, v39
	v_cvt_pk_bf16_f32 v35, v40, v41
	v_cvt_pk_bf16_f32 v36, v42, v43
	v_cvt_pk_bf16_f32 v37, v44, v45
	global_store_dwordx4 v[52:53], v[34:37], off
	s_nop 1
	v_xor_b32_e32 v34, 0x80000000, v46
	s_nop 1
	v_permlane16_swap_b32_e32 v46, v34
	s_nop 0
	v_add_f32_e32 v35, v46, v34
	v_and_b32_e32 v34, 0x7fffffff, v35
	v_or_b32_e32 v35, 0x80000000, v35
	s_nop 1
	v_permlane32_swap_b32_e32 v34, v35
	s_and_saveexec_b64 s[12:13], s[2:3]
	s_cbranch_execz .LBB0_1587
	v_add_f32_e32 v34, v34, v35
	v_and_b32_e32 v36, 0x7fffffff, v34
	v_add_u32_e32 v34, 0x90, v154
	v_ashrrev_i32_e32 v35, 31, v34
	v_readlane_b32 s14, v254, 51
	v_lshlrev_b64 v[34:35], 6, v[34:35]
	v_readlane_b32 s15, v254, 52
	s_lshl_b32 s72, s16, 2
	s_nop 0
	v_lshl_add_u64 v[34:35], s[14:15], 0, v[34:35]
	v_lshl_add_u64 v[34:35], s[8:9], 2, v[34:35]
	v_lshl_add_u64 v[34:35], v[34:35], 0, s[72:73]
	global_store_dword v[34:35], v36, off
; __device__ __forceinline__ u32x4 pack8(const float (&v)[8]) { u32x4 w; w.x = pk2(v[0], v[1]); w.y = pk2(v[2], v[3]); w.z = pk2(v[4], v[5]); w.w = pk2(v[6], v[7]); return w; }
; __device__ __forceinline__ float xsum16p(float x) { const unsigned u = __builtin_bit_cast(unsigned, x); const auto r = __builtin_amdgcn_permlane16_swap(u, u ^ 0x80000000u, false, false); unsigned r0 = r[0], r1 = r[1]; asm("" : "+v"(r0), "+v"(r1)); return fabsf(__builtin_bit_cast(float, r0) + __builtin_bit_cast(float, r1)); }
; __device__ __forceinline__ float xsum32p(float x) { const unsigned u = __builtin_bit_cast(unsigned, x); const auto r = __builtin_amdgcn_permlane32_swap(u, u ^ 0x80000000u, false, false); unsigned r0 = r[0], r1 = r[1]; asm("" : "+v"(r0), "+v"(r1)); return fabsf(__builtin_bit_cast(float, r0) + __builtin_bit_cast(float, r1)); }
;     __device__ __forceinline__ void row_group(Acc& acc, const int ai, const int m, const float (&xo0)[8], const float (&xo1)[8], bf16_t* xb0, const int row0, const int pn, const int wc, const int fq) const {
;         float ssq = 0.f;
; #pragma unroll
;         for (int bj = 0; bj < 2; ++bj) {
;             float v[8];
; #pragma unroll
;             for (int e = 0; e < 4; ++e) { const float a0 = bj ? xo1[e] : xo0[e], a1 = bj ? xo1[4 + e] : xo0[4 + e]; v[e] = dry ? a0 : a0 + acc[ai][bj][m][0][e]; v[4 + e] = dry ? a1 : a1 + acc[ai][bj][m][1][e]; }
; #pragma unroll
;             for (int e = 0; e < 8; ++e) ssq += v[e] * v[e];
;             gst<u32x4>(xb0 + (size_t)(ai * HALF + m * 16) * DM + bj * HALF, pack8(v));
;         }
;         ssq = xsum32p(xsum16p(ssq));
;         if (fq == 0) gst<float>(ss_next + (size_t)(row0 + ai * HALF + m * 16) * 16 + pn * 4 + wc, ssq);
;     }
.LBB0_1587:
	s_or_b64 exec, exec, s[12:13]
	v_lshlrev_b32_e32 v38, 16, v78
	v_and_b32_e32 v39, 0xffff0000, v78
	v_pk_add_f32 v[30:31], v[30:31], v[38:39]
	v_lshlrev_b32_e32 v38, 16, v80
	v_and_b32_e32 v39, 0xffff0000, v80
	v_pk_add_f32 v[38:39], v[26:27], v[38:39]
	v_lshlrev_b32_e32 v26, 16, v79
	v_and_b32_e32 v27, 0xffff0000, v79
	v_pk_add_f32 v[32:33], v[32:33], v[26:27]
	v_lshlrev_b32_e32 v26, 16, v81
	v_and_b32_e32 v27, 0xffff0000, v81
	s_mov_b64 s[12:13], 0x50000
	v_pk_add_f32 v[40:41], v[28:29], v[26:27]
	v_lshl_add_u64 v[34:35], v[156:157], 0, s[12:13]
	v_pk_mul_f32 v[42:43], v[30:31], v[30:31]
	v_cvt_pk_bf16_f32 v26, v30, v31
	v_cvt_pk_bf16_f32 v27, v32, v33
	v_cvt_pk_bf16_f32 v28, v38, v39
	v_cvt_pk_bf16_f32 v29, v40, v41
	v_pk_mul_f32 v[44:45], v[32:33], v[32:33]
	global_store_dwordx4 v[34:35], v[26:29], off
	v_add_f32_e32 v34, v42, v43
	v_add_f32_e32 v34, v44, v34
	v_pk_mul_f32 v[46:47], v[38:39], v[38:39]
	v_lshlrev_b32_e32 v26, 16, v74
	v_and_b32_e32 v27, 0xffff0000, v74
	v_add_f32_e32 v34, v45, v34
	v_pk_add_f32 v[22:23], v[22:23], v[26:27]
	v_lshlrev_b32_e32 v26, 16, v76
	v_and_b32_e32 v27, 0xffff0000, v76
	v_add_f32_e32 v34, v46, v34
	v_pk_mul_f32 v[48:49], v[40:41], v[40:41]
	v_pk_add_f32 v[26:27], v[18:19], v[26:27]
	v_lshlrev_b32_e32 v18, 16, v75
	v_and_b32_e32 v19, 0xffff0000, v75
	v_add_f32_e32 v34, v47, v34
	v_pk_add_f32 v[24:25], v[24:25], v[18:19]
	v_lshlrev_b32_e32 v18, 16, v77
	v_and_b32_e32 v19, 0xffff0000, v77
	v_add_f32_e32 v34, v48, v34
	v_pk_add_f32 v[28:29], v[20:21], v[18:19]
	v_pk_mul_f32 v[18:19], v[22:23], v[22:23]
	v_add_f32_e32 v34, v49, v34
	v_add_f32_e32 v18, v18, v34
	v_pk_mul_f32 v[20:21], v[24:25], v[24:25]
	v_add_f32_e32 v18, v19, v18
	v_add_f32_e32 v18, v20, v18
	v_pk_mul_f32 v[30:31], v[26:27], v[26:27]
	v_add_f32_e32 v18, v21, v18
	v_add_f32_e32 v18, v30, v18
	v_pk_mul_f32 v[32:33], v[28:29], v[28:29]
	v_add_f32_e32 v18, v31, v18
	s_mov_b64 s[12:13], 0x50100
	v_add_f32_e32 v18, v32, v18
	v_lshl_add_u64 v[36:37], v[156:157], 0, s[12:13]
	v_add_f32_e32 v30, v33, v18
	v_cvt_pk_bf16_f32 v18, v22, v23
	v_cvt_pk_bf16_f32 v19, v24, v25
	v_cvt_pk_bf16_f32 v20, v26, v27
	v_cvt_pk_bf16_f32 v21, v28, v29
	global_store_dwordx4 v[36:37], v[18:21], off
	s_nop 1
	v_xor_b32_e32 v18, 0x80000000, v30
	s_nop 1
	v_permlane16_swap_b32_e32 v30, v18
	s_nop 0
	v_add_f32_e32 v19, v30, v18
	v_and_b32_e32 v18, 0x7fffffff, v19
	v_or_b32_e32 v19, 0x80000000, v19
	s_nop 1
	v_permlane32_swap_b32_e32 v18, v19
	s_and_saveexec_b64 s[12:13], s[2:3]
	s_cbranch_execz .LBB0_1589
	v_add_f32_e32 v18, v18, v19
	v_and_b32_e32 v20, 0x7fffffff, v18
	v_add_u32_e32 v18, 0xa0, v154
	v_ashrrev_i32_e32 v19, 31, v18
	v_readlane_b32 s14, v254, 51
	v_lshlrev_b64 v[18:19], 6, v[18:19]
	v_readlane_b32 s15, v254, 52
	s_lshl_b32 s72, s16, 2
	s_nop 0
	v_lshl_add_u64 v[18:19], s[14:15], 0, v[18:19]
	v_lshl_add_u64 v[18:19], s[8:9], 2, v[18:19]
	v_lshl_add_u64 v[18:19], v[18:19], 0, s[72:73]
	global_store_dword v[18:19], v20, off
.LBB0_1589:
	s_or_b64 exec, exec, s[12:13]
	v_lshlrev_b32_e32 v22, 16, v70
	v_and_b32_e32 v23, 0xffff0000, v70
	v_pk_add_f32 v[14:15], v[14:15], v[22:23]
	v_lshlrev_b32_e32 v22, 16, v72
	v_and_b32_e32 v23, 0xffff0000, v72
	v_pk_add_f32 v[22:23], v[10:11], v[22:23]
	v_lshlrev_b32_e32 v10, 16, v71
	v_and_b32_e32 v11, 0xffff0000, v71
	v_pk_add_f32 v[16:17], v[16:17], v[10:11]
	v_lshlrev_b32_e32 v10, 16, v73
	v_and_b32_e32 v11, 0xffff0000, v73
	s_mov_b64 s[12:13], 0x58000
	v_pk_add_f32 v[24:25], v[12:13], v[10:11]
	v_lshl_add_u64 v[18:19], v[156:157], 0, s[12:13]
	v_pk_mul_f32 v[26:27], v[14:15], v[14:15]
	v_cvt_pk_bf16_f32 v10, v14, v15
	v_cvt_pk_bf16_f32 v11, v16, v17
	v_cvt_pk_bf16_f32 v12, v22, v23
	v_cvt_pk_bf16_f32 v13, v24, v25
	v_pk_mul_f32 v[28:29], v[16:17], v[16:17]
	global_store_dwordx4 v[18:19], v[10:13], off
	v_add_f32_e32 v18, v26, v27
	v_add_f32_e32 v18, v28, v18
	v_pk_mul_f32 v[30:31], v[22:23], v[22:23]
	v_lshlrev_b32_e32 v10, 16, v66
	v_and_b32_e32 v11, 0xffff0000, v66
	v_add_f32_e32 v18, v29, v18
	v_pk_add_f32 v[6:7], v[6:7], v[10:11]
	v_lshlrev_b32_e32 v10, 16, v68
	v_and_b32_e32 v11, 0xffff0000, v68
	v_add_f32_e32 v18, v30, v18
	v_pk_mul_f32 v[32:33], v[24:25], v[24:25]
	v_pk_add_f32 v[10:11], v[2:3], v[10:11]
	v_lshlrev_b32_e32 v2, 16, v67
	v_and_b32_e32 v3, 0xffff0000, v67
	v_add_f32_e32 v18, v31, v18
	v_pk_add_f32 v[8:9], v[8:9], v[2:3]
	v_lshlrev_b32_e32 v2, 16, v69
	v_and_b32_e32 v3, 0xffff0000, v69
	v_add_f32_e32 v18, v32, v18
	v_pk_add_f32 v[12:13], v[4:5], v[2:3]
	v_pk_mul_f32 v[2:3], v[6:7], v[6:7]
	v_add_f32_e32 v18, v33, v18
	v_add_f32_e32 v2, v2, v18
	v_pk_mul_f32 v[4:5], v[8:9], v[8:9]
	v_add_f32_e32 v2, v3, v2
	v_add_f32_e32 v2, v4, v2
	v_pk_mul_f32 v[14:15], v[10:11], v[10:11]
	v_add_f32_e32 v2, v5, v2
	v_add_f32_e32 v2, v14, v2
	v_pk_mul_f32 v[16:17], v[12:13], v[12:13]
	v_add_f32_e32 v2, v15, v2
	s_mov_b64 s[12:13], 0x58100
	v_add_f32_e32 v2, v16, v2
	v_lshl_add_u64 v[20:21], v[156:157], 0, s[12:13]
	v_add_f32_e32 v14, v17, v2
	v_cvt_pk_bf16_f32 v2, v6, v7
	v_cvt_pk_bf16_f32 v3, v8, v9
	v_cvt_pk_bf16_f32 v4, v10, v11
	v_cvt_pk_bf16_f32 v5, v12, v13
	global_store_dwordx4 v[20:21], v[2:5], off
	s_nop 1
	v_xor_b32_e32 v2, 0x80000000, v14
	s_nop 1
	v_permlane16_swap_b32_e32 v14, v2
	s_nop 0
	v_add_f32_e32 v3, v14, v2
	v_and_b32_e32 v2, 0x7fffffff, v3
	v_or_b32_e32 v3, 0x80000000, v3
	s_nop 1
	v_permlane32_swap_b32_e32 v2, v3
	s_and_saveexec_b64 s[12:13], s[2:3]
	s_cbranch_execz .LBB0_1591
	v_add_f32_e32 v2, v2, v3
	v_and_b32_e32 v4, 0x7fffffff, v2
	v_add_u32_e32 v2, 0xb0, v154
	v_ashrrev_i32_e32 v3, 31, v2
	v_readlane_b32 s2, v254, 51
	v_lshlrev_b64 v[2:3], 6, v[2:3]
	v_readlane_b32 s3, v254, 52
	s_lshl_b32 s72, s16, 2
	s_nop 0
	v_lshl_add_u64 v[2:3], s[2:3], 0, v[2:3]
	v_lshl_add_u64 v[2:3], s[8:9], 2, v[2:3]
	v_lshl_add_u64 v[2:3], v[2:3], 0, s[72:73]
	global_store_dword v[2:3], v4, off
